# kprio4 + the nine GEMM K-loop heads aligned to 64-byte instruction-cache lines
# speedup vs baseline: 1.0053x; 1.0007x over previous
; #define PG8_WAIT_V(n) asm volatile("s_waitcnt vmcnt(" #n ")" ::: "memory")
; #define PG8_BAR __builtin_amdgcn_s_barrier()
; template <class Epi, bool ALIGN_EPI = PG8_ALIGN>
; __device__ __forceinline__ void gemm_phase(LAS unsigned char* lds, const Gemm g, const StaticOrder& S, const Epi& E) {
;     ...
;         const bool has_next = S.next(ui + 1, nxt);
;         const char* nA = has_next ? (const char*)g.A + (size_t)nxt.pm * tstepA : cA; const char* nB = has_next ? (const char*)g.Bt + (size_t)nxt.pn * tstepB : cB;
;         for (int t = 0; t < nt; t += 2) {
;             const bool last = (t == nt - 2);
;             const char* a1 = cA + (size_t)(t + 1) * kstep;
;             const char* a2 = last ? nA : cA + (size_t)(t + 2) * kstep; const char* b2 = last ? nB : cB + (size_t)(t + 2) * kstep;
;             const char* a3 = a2 + kstep; const char* b3 = b2 + kstep;
;             PG8_LDB(B0, 0, 0); PG8_LDB(B1, 0, 1); PG8_SCHED; PG8_LDA(At, 0, 0); PG8_STAGE(PG8_SA(1, 1), a1 + hstepA, voffA);
;             PG8_WAIT_V(8); PG8_WAIT_L(0); PG8_BAR; PG8_MMA(0, 0, At, B0); PG8_MMA(0, 1, At, B1); PG8_BAR; PG8_SCHED;
;             PG8_LDA(At, 0, 1); PG8_STAGE(PG8_SB(0, 0), b2, voffB); PG8_STAGE(PG8_SB(0, 1), b2 + hstepB, voffB); PG8_STAGE(PG8_SA(0, 0), a2, voffA);
;             PG8_WAIT_V(8); PG8_WAIT_L(0); PG8_BAR; PG8_MMA(1, 0, At, B0); PG8_MMA(1, 1, At, B1); PG8_BAR; PG8_SCHED;
;             PG8_LDB(B0, 1, 0); PG8_LDB(B1, 1, 1); PG8_SCHED; PG8_LDA(At, 1, 0); PG8_STAGE(PG8_SA(0, 1), a2 + hstepA, voffA);
;             PG8_WAIT_V(8); PG8_WAIT_L(0); PG8_BAR; PG8_MMA(0, 0, At, B0); PG8_MMA(0, 1, At, B1); PG8_BAR; PG8_SCHED;
;             PG8_LDA(At, 1, 1); PG8_STAGE(PG8_SB(1, 0), b3, voffB); PG8_STAGE(PG8_SB(1, 1), b3 + hstepB, voffB); PG8_STAGE(PG8_SA(1, 0), a3, voffA);
;             PG8_WAIT_V(8); PG8_WAIT_L(0); PG8_BAR; PG8_MMA(1, 0, At, B0); PG8_MMA(1, 1, At, B1); PG8_BAR; PG8_SCHED;
;         }
;         if (ALIGN_EPI) { if (wr == 0) PG8_BAR; }
;         E(acc, cur, wr, wc, fr, fq);
;         if (!has_next) break;
; #pragma unroll
;         for (int a = 0; a < 2; ++a)
; #pragma unroll
;             for (int b = 0; b < 2; ++b)
; #pragma unroll
;                 for (int m = 0; m < 4; ++m)
; #pragma unroll
;                     for (int n = 0; n < 2; ++n) acc[a][b][m][n] = (f32x4){0.f, 0.f, 0.f, 0.f};
;         cur = nxt; cA = nA; cB = nB; ++ui;
.LBB0_217:
	s_ashr_i32 s15, s14, 31
	s_lshl_b64 s[40:41], s[14:15], 20
	s_add_u32 s40, s58, s40
	v_mov_b32_e32 v127, 0
	s_addc_u32 s41, s59, s41
	s_andn2_b64 vcc, exec, s[10:11]
	v_mov_b32_e32 v126, v127
	v_mov_b32_e32 v125, v127
	v_mov_b32_e32 v124, v127
	v_mov_b32_e32 v119, v127
	v_mov_b32_e32 v118, v127
	v_mov_b32_e32 v117, v127
	v_mov_b32_e32 v116, v127
	v_mov_b32_e32 v111, v127
	v_mov_b32_e32 v110, v127
	v_mov_b32_e32 v109, v127
	v_mov_b32_e32 v108, v127
	v_mov_b32_e32 v103, v127
	v_mov_b32_e32 v102, v127
	v_mov_b32_e32 v101, v127
	v_mov_b32_e32 v100, v127
	v_mov_b32_e32 v95, v127
	v_mov_b32_e32 v94, v127
	v_mov_b32_e32 v93, v127
	v_mov_b32_e32 v92, v127
	v_mov_b32_e32 v87, v127
	v_mov_b32_e32 v86, v127
	v_mov_b32_e32 v85, v127
	v_mov_b32_e32 v84, v127
	v_mov_b32_e32 v79, v127
	v_mov_b32_e32 v78, v127
	v_mov_b32_e32 v77, v127
	v_mov_b32_e32 v76, v127
	v_mov_b32_e32 v71, v127
	v_mov_b32_e32 v70, v127
	v_mov_b32_e32 v69, v127
	v_mov_b32_e32 v68, v127
	v_mov_b32_e32 v123, v127
	v_mov_b32_e32 v122, v127
	v_mov_b32_e32 v121, v127
	v_mov_b32_e32 v120, v127
	v_mov_b32_e32 v115, v127
	v_mov_b32_e32 v114, v127
	v_mov_b32_e32 v113, v127
	v_mov_b32_e32 v112, v127
	v_mov_b32_e32 v107, v127
	v_mov_b32_e32 v106, v127
	v_mov_b32_e32 v105, v127
	v_mov_b32_e32 v104, v127
	v_mov_b32_e32 v99, v127
	v_mov_b32_e32 v98, v127
	v_mov_b32_e32 v97, v127
	v_mov_b32_e32 v96, v127
	v_mov_b32_e32 v91, v127
	v_mov_b32_e32 v90, v127
	v_mov_b32_e32 v89, v127
	v_mov_b32_e32 v88, v127
	v_mov_b32_e32 v83, v127
	v_mov_b32_e32 v82, v127
	v_mov_b32_e32 v81, v127
	v_mov_b32_e32 v80, v127
	v_mov_b32_e32 v75, v127
	v_mov_b32_e32 v74, v127
	v_mov_b32_e32 v73, v127
	v_mov_b32_e32 v72, v127
	v_mov_b32_e32 v67, v127
	v_mov_b32_e32 v66, v127
	v_mov_b32_e32 v65, v127
	v_mov_b32_e32 v64, v127
	v_mov_b32_e32 v63, v127
	v_mov_b32_e32 v62, v127
	v_mov_b32_e32 v61, v127
	v_mov_b32_e32 v60, v127
	v_mov_b32_e32 v55, v127
	v_mov_b32_e32 v54, v127
	v_mov_b32_e32 v53, v127
	v_mov_b32_e32 v52, v127
	v_mov_b32_e32 v47, v127
	v_mov_b32_e32 v46, v127
	v_mov_b32_e32 v45, v127
	v_mov_b32_e32 v44, v127
	v_mov_b32_e32 v39, v127
	v_mov_b32_e32 v38, v127
	v_mov_b32_e32 v37, v127
	v_mov_b32_e32 v36, v127
	v_mov_b32_e32 v31, v127
	v_mov_b32_e32 v30, v127
	v_mov_b32_e32 v29, v127
	v_mov_b32_e32 v28, v127
	v_mov_b32_e32 v23, v127
	v_mov_b32_e32 v22, v127
	v_mov_b32_e32 v21, v127
	v_mov_b32_e32 v20, v127
	v_mov_b32_e32 v15, v127
	v_mov_b32_e32 v14, v127
	v_mov_b32_e32 v13, v127
	v_mov_b32_e32 v12, v127
	v_mov_b32_e32 v7, v127
	v_mov_b32_e32 v6, v127
	v_mov_b32_e32 v5, v127
	v_mov_b32_e32 v4, v127
	v_mov_b32_e32 v59, v127
	v_mov_b32_e32 v58, v127
	v_mov_b32_e32 v57, v127
	v_mov_b32_e32 v56, v127
	v_mov_b32_e32 v51, v127
	v_mov_b32_e32 v50, v127
	v_mov_b32_e32 v49, v127
	v_mov_b32_e32 v48, v127
	v_mov_b32_e32 v43, v127
	v_mov_b32_e32 v42, v127
	v_mov_b32_e32 v41, v127
	v_mov_b32_e32 v40, v127
	v_mov_b32_e32 v35, v127
	v_mov_b32_e32 v34, v127
	v_mov_b32_e32 v33, v127
	v_mov_b32_e32 v32, v127
	v_mov_b32_e32 v27, v127
	v_mov_b32_e32 v26, v127
	v_mov_b32_e32 v25, v127
	v_mov_b32_e32 v24, v127
	v_mov_b32_e32 v19, v127
	v_mov_b32_e32 v18, v127
	v_mov_b32_e32 v17, v127
	v_mov_b32_e32 v16, v127
	v_mov_b32_e32 v11, v127
	v_mov_b32_e32 v10, v127
	v_mov_b32_e32 v9, v127
	v_mov_b32_e32 v8, v127
	v_mov_b32_e32 v3, v127
	v_mov_b32_e32 v2, v127
	v_mov_b32_e32 v1, v127
	v_mov_b32_e32 v0, v127
	s_cbranch_vccnz .LBB0_220
	s_and_b64 s[2:3], s[2:3], exec
	s_cselect_b32 s15, s41, s37
	s_cselect_b32 s34, s40, s36
	s_add_u32 s2, s36, 0x80080
	s_addc_u32 s3, s37, 0
	s_add_u32 s36, s24, 0x100
	v_mov_b32_e32 v0, 0
	s_addc_u32 s37, s25, 0
	s_mov_b32 s24, 0
	v_mov_b32_e32 v1, v0
	v_mov_b32_e32 v2, v0
	v_mov_b32_e32 v3, v0
	v_mov_b32_e32 v8, v0
	v_mov_b32_e32 v9, v0
	v_mov_b32_e32 v10, v0
	v_mov_b32_e32 v11, v0
	v_mov_b32_e32 v16, v0
	v_mov_b32_e32 v17, v0
	v_mov_b32_e32 v18, v0
	v_mov_b32_e32 v19, v0
	v_mov_b32_e32 v24, v0
	v_mov_b32_e32 v25, v0
	v_mov_b32_e32 v26, v0
	v_mov_b32_e32 v27, v0
	v_mov_b32_e32 v32, v0
	v_mov_b32_e32 v33, v0
	v_mov_b32_e32 v34, v0
	v_mov_b32_e32 v35, v0
	v_mov_b32_e32 v40, v0
	v_mov_b32_e32 v41, v0
	v_mov_b32_e32 v42, v0
	v_mov_b32_e32 v43, v0
	v_mov_b32_e32 v48, v0
	v_mov_b32_e32 v49, v0
	v_mov_b32_e32 v50, v0
	v_mov_b32_e32 v51, v0
	v_mov_b32_e32 v56, v0
	v_mov_b32_e32 v57, v0
	v_mov_b32_e32 v58, v0
	v_mov_b32_e32 v59, v0
	v_mov_b32_e32 v4, v0
	v_mov_b32_e32 v5, v0
	v_mov_b32_e32 v6, v0
	v_mov_b32_e32 v7, v0
	v_mov_b32_e32 v12, v0
	v_mov_b32_e32 v13, v0
	v_mov_b32_e32 v14, v0
	v_mov_b32_e32 v15, v0
	v_mov_b32_e32 v20, v0
	v_mov_b32_e32 v21, v0
	v_mov_b32_e32 v22, v0
	v_mov_b32_e32 v23, v0
	v_mov_b32_e32 v28, v0
	v_mov_b32_e32 v29, v0
	v_mov_b32_e32 v30, v0
	v_mov_b32_e32 v31, v0
	v_mov_b32_e32 v36, v0
	v_mov_b32_e32 v37, v0
	v_mov_b32_e32 v38, v0
	v_mov_b32_e32 v39, v0
	v_mov_b32_e32 v44, v0
	v_mov_b32_e32 v45, v0
	v_mov_b32_e32 v46, v0
	v_mov_b32_e32 v47, v0
	v_mov_b32_e32 v52, v0
	v_mov_b32_e32 v53, v0
	v_mov_b32_e32 v54, v0
	v_mov_b32_e32 v55, v0
	v_mov_b32_e32 v60, v0
	v_mov_b32_e32 v61, v0
	v_mov_b32_e32 v62, v0
	v_mov_b32_e32 v63, v0
	v_mov_b32_e32 v64, v0
	v_mov_b32_e32 v65, v0
	v_mov_b32_e32 v66, v0
	v_mov_b32_e32 v67, v0
	v_mov_b32_e32 v72, v0
	v_mov_b32_e32 v73, v0
	v_mov_b32_e32 v74, v0
	v_mov_b32_e32 v75, v0
	v_mov_b32_e32 v80, v0
	v_mov_b32_e32 v81, v0
	v_mov_b32_e32 v82, v0
	v_mov_b32_e32 v83, v0
	v_mov_b32_e32 v88, v0
	v_mov_b32_e32 v89, v0
	v_mov_b32_e32 v90, v0
	v_mov_b32_e32 v91, v0
	v_mov_b32_e32 v96, v0
	v_mov_b32_e32 v97, v0
	v_mov_b32_e32 v98, v0
	v_mov_b32_e32 v99, v0
	v_mov_b32_e32 v104, v0
	v_mov_b32_e32 v105, v0
	v_mov_b32_e32 v106, v0
	v_mov_b32_e32 v107, v0
	v_mov_b32_e32 v112, v0
	v_mov_b32_e32 v113, v0
	v_mov_b32_e32 v114, v0
	v_mov_b32_e32 v115, v0
	v_mov_b32_e32 v120, v0
	v_mov_b32_e32 v121, v0
	v_mov_b32_e32 v122, v0
	v_mov_b32_e32 v123, v0
	v_mov_b32_e32 v68, v0
	v_mov_b32_e32 v69, v0
	v_mov_b32_e32 v70, v0
	v_mov_b32_e32 v71, v0
	v_mov_b32_e32 v76, v0
	v_mov_b32_e32 v77, v0
	v_mov_b32_e32 v78, v0
	v_mov_b32_e32 v79, v0
	v_mov_b32_e32 v84, v0
	v_mov_b32_e32 v85, v0
	v_mov_b32_e32 v86, v0
	v_mov_b32_e32 v87, v0
	v_mov_b32_e32 v92, v0
	v_mov_b32_e32 v93, v0
	v_mov_b32_e32 v94, v0
	v_mov_b32_e32 v95, v0
	v_mov_b32_e32 v100, v0
	v_mov_b32_e32 v101, v0
	v_mov_b32_e32 v102, v0
	v_mov_b32_e32 v103, v0
	v_mov_b32_e32 v108, v0
	v_mov_b32_e32 v109, v0
	v_mov_b32_e32 v110, v0
	v_mov_b32_e32 v111, v0
	v_mov_b32_e32 v116, v0
	v_mov_b32_e32 v117, v0
	v_mov_b32_e32 v118, v0
	v_mov_b32_e32 v119, v0
	v_mov_b32_e32 v124, v0
	v_mov_b32_e32 v125, v0
	v_mov_b32_e32 v126, v0
	v_mov_b32_e32 v127, v0
	.p2align	6

; #define PG8_STAGE(bufoff, gbase, voff) do { _Pragma("unroll") for (int _i = 0; _i < 2; ++_i) \
;         __builtin_amdgcn_global_load_lds((const unsigned*)((const char*)(gbase) + (voff)[_i]), (LAS unsigned*)(lds + (bufoff) + ldsw + _i * 8192), 16, 0, 0); } while (0)
; #define PG8_WAIT_V(n) asm volatile("s_waitcnt vmcnt(" #n ")" ::: "memory")
; #define PG8_BAR __builtin_amdgcn_s_barrier()
; template <class Epi, bool ALIGN_EPI = PG8_ALIGN>
; __device__ __forceinline__ void gemm_phase(LAS unsigned char* lds, const Gemm g, const StaticOrder& S, const Epi& E) {
;     ...
;     f32x4 acc[2][2][4][2];
; #pragma unroll
;     for (int a = 0; a < 2; ++a)
; #pragma unroll
;         for (int b = 0; b < 2; ++b)
; #pragma unroll
;             for (int m = 0; m < 4; ++m)
; #pragma unroll
;                 for (int n = 0; n < 2; ++n) acc[a][b][m][n] = (f32x4){0.f, 0.f, 0.f, 0.f};
;     bf16x8 At[4][2], B0[2][2], B1[2][2];
;     const char* cA = (const char*)g.A + (size_t)cur.pm * tstepA; const char* cB = (const char*)g.Bt + (size_t)cur.pn * tstepB;
;     PG8_STAGE(PG8_SB(0, 0), cB, voffB); PG8_STAGE(PG8_SB(0, 1), cB + hstepB, voffB); PG8_STAGE(PG8_SA(0, 0), cA, voffA); PG8_STAGE(PG8_SA(0, 1), cA + hstepA, voffA);
;     if (wr == 1) PG8_BAR;
;     PG8_WAIT_V(2); PG8_BAR;
;     PG8_STAGE(PG8_SB(1, 0), cB + kstep, voffB); PG8_STAGE(PG8_SA(1, 0), cA + kstep, voffA); PG8_STAGE(PG8_SB(1, 1), cB + hstepB + kstep, voffB);
;     PG8_WAIT_V(6); PG8_BAR;
;     for (;;) {
;         const bool has_next = S.next(ui + 1, nxt);
;         const char* nA = has_next ? (const char*)g.A + (size_t)nxt.pm * tstepA : cA; const char* nB = has_next ? (const char*)g.Bt + (size_t)nxt.pn * tstepB : cB;
;         for (int t = 0; t < nt; t += 2) {
.LBB0_293:
	v_mov_b32_e32 v127, 0
	s_andn2_b64 vcc, exec, s[12:13]
	v_mov_b32_e32 v126, 0
	v_mov_b32_e32 v125, 0
	v_mov_b32_e32 v124, 0
	v_mov_b32_e32 v123, 0
	v_mov_b32_e32 v122, 0
	v_mov_b32_e32 v121, 0
	v_mov_b32_e32 v120, 0
	v_mov_b32_e32 v101, 0
	v_mov_b32_e32 v100, 0
	v_mov_b32_e32 v103, 0
	v_mov_b32_e32 v102, 0
	v_mov_b32_e32 v109, 0
	v_mov_b32_e32 v108, 0
	v_mov_b32_e32 v111, 0
	v_mov_b32_e32 v110, 0
	v_mov_b32_e32 v85, 0
	v_mov_b32_e32 v84, 0
	v_mov_b32_e32 v87, 0
	v_mov_b32_e32 v86, 0
	v_mov_b32_e32 v93, 0
	v_mov_b32_e32 v92, 0
	v_mov_b32_e32 v95, 0
	v_mov_b32_e32 v94, 0
	v_mov_b32_e32 v73, 0
	v_mov_b32_e32 v72, 0
	v_mov_b32_e32 v75, 0
	v_mov_b32_e32 v74, 0
	v_mov_b32_e32 v77, 0
	v_mov_b32_e32 v76, 0
	v_mov_b32_e32 v79, 0
	v_mov_b32_e32 v78, 0
	v_mov_b32_e32 v139, 0
	v_mov_b32_e32 v138, 0
	v_mov_b32_e32 v141, 0
	v_mov_b32_e32 v140, 0
	v_mov_b32_e32 v143, 0
	v_mov_b32_e32 v142, 0
	v_mov_b32_e32 v145, 0
	v_mov_b32_e32 v144, 0
	v_mov_b32_e32 v113, 0
	v_mov_b32_e32 v112, 0
	v_mov_b32_e32 v115, 0
	v_mov_b32_e32 v114, 0
	v_mov_b32_e32 v117, 0
	v_mov_b32_e32 v116, 0
	v_mov_b32_e32 v119, 0
	v_mov_b32_e32 v118, 0
	v_mov_b32_e32 v97, 0
	v_mov_b32_e32 v96, 0
	v_mov_b32_e32 v99, 0
	v_mov_b32_e32 v98, 0
	v_mov_b32_e32 v105, 0
	v_mov_b32_e32 v104, 0
	v_mov_b32_e32 v107, 0
	v_mov_b32_e32 v106, 0
	v_mov_b32_e32 v71, 0
	v_mov_b32_e32 v70, 0
	v_mov_b32_e32 v69, 0
	v_mov_b32_e32 v68, 0
	v_mov_b32_e32 v67, 0
	v_mov_b32_e32 v66, 0
	v_mov_b32_e32 v65, 0
	v_mov_b32_e32 v64, 0
	v_mov_b32_e32 v63, 0
	v_mov_b32_e32 v62, 0
	v_mov_b32_e32 v61, 0
	v_mov_b32_e32 v60, 0
	v_mov_b32_e32 v59, 0
	v_mov_b32_e32 v58, 0
	v_mov_b32_e32 v57, 0
	v_mov_b32_e32 v56, 0
	v_mov_b32_e32 v37, 0
	v_mov_b32_e32 v36, 0
	v_mov_b32_e32 v39, 0
	v_mov_b32_e32 v38, 0
	v_mov_b32_e32 v45, 0
	v_mov_b32_e32 v44, 0
	v_mov_b32_e32 v47, 0
	v_mov_b32_e32 v46, 0
	v_mov_b32_e32 v21, 0
	v_mov_b32_e32 v20, 0
	v_mov_b32_e32 v23, 0
	v_mov_b32_e32 v22, 0
	v_mov_b32_e32 v29, 0
	v_mov_b32_e32 v28, 0
	v_mov_b32_e32 v31, 0
	v_mov_b32_e32 v30, 0
	v_mov_b32_e32 v9, 0
	v_mov_b32_e32 v8, 0
	v_mov_b32_e32 v11, 0
	v_mov_b32_e32 v10, 0
	v_mov_b32_e32 v13, 0
	v_mov_b32_e32 v12, 0
	v_mov_b32_e32 v15, 0
	v_mov_b32_e32 v14, 0
	v_mov_b32_e32 v81, 0
	v_mov_b32_e32 v80, 0
	v_mov_b32_e32 v83, 0
	v_mov_b32_e32 v82, 0
	v_mov_b32_e32 v89, 0
	v_mov_b32_e32 v88, 0
	v_mov_b32_e32 v91, 0
	v_mov_b32_e32 v90, 0
	v_mov_b32_e32 v49, 0
	v_mov_b32_e32 v48, 0
	v_mov_b32_e32 v51, 0
	v_mov_b32_e32 v50, 0
	v_mov_b32_e32 v53, 0
	v_mov_b32_e32 v52, 0
	v_mov_b32_e32 v55, 0
	v_mov_b32_e32 v54, 0
	v_mov_b32_e32 v33, 0
	v_mov_b32_e32 v32, 0
	v_mov_b32_e32 v35, 0
	v_mov_b32_e32 v34, 0
	v_mov_b32_e32 v41, 0
	v_mov_b32_e32 v40, 0
	v_mov_b32_e32 v43, 0
	v_mov_b32_e32 v42, 0
	v_mov_b32_e32 v7, 0
	v_mov_b32_e32 v6, 0
	v_mov_b32_e32 v5, 0
	v_mov_b32_e32 v4, 0
	v_mov_b32_e32 v3, 0
	v_mov_b32_e32 v2, 0
	v_mov_b32_e32 v1, 0
	v_mov_b32_e32 v0, 0
	s_cbranch_vccnz .LBB0_297
	s_add_u32 s51, s36, 0x100
	v_mov_b32_e32 v0, 0
	s_addc_u32 s52, s37, 0
	s_mov_b32 s38, 0
	v_mov_b32_e32 v1, v0
	v_mov_b32_e32 v2, v0
	v_mov_b32_e32 v3, v0
	v_mov_b32_e32 v4, v0
	v_mov_b32_e32 v5, v0
	v_mov_b32_e32 v6, v0
	v_mov_b32_e32 v7, v0
	v_mov_b32_e32 v8, v0
	v_mov_b32_e32 v9, v0
	v_mov_b32_e32 v10, v0
	v_mov_b32_e32 v11, v0
	v_mov_b32_e32 v12, v0
	v_mov_b32_e32 v13, v0
	v_mov_b32_e32 v14, v0
	v_mov_b32_e32 v15, v0
	v_mov_b32_e32 v20, v0
	v_mov_b32_e32 v21, v0
	v_mov_b32_e32 v22, v0
	v_mov_b32_e32 v23, v0
	v_mov_b32_e32 v28, v0
	v_mov_b32_e32 v29, v0
	v_mov_b32_e32 v30, v0
	v_mov_b32_e32 v31, v0
	v_mov_b32_e32 v36, v0
	v_mov_b32_e32 v37, v0
	v_mov_b32_e32 v38, v0
	v_mov_b32_e32 v39, v0
	v_mov_b32_e32 v44, v0
	v_mov_b32_e32 v45, v0
	v_mov_b32_e32 v46, v0
	v_mov_b32_e32 v47, v0
	v_mov_b32_e32 v16, v0
	v_mov_b32_e32 v17, v0
	v_mov_b32_e32 v18, v0
	v_mov_b32_e32 v19, v0
	v_mov_b32_e32 v24, v0
	v_mov_b32_e32 v25, v0
	v_mov_b32_e32 v26, v0
	v_mov_b32_e32 v27, v0
	v_mov_b32_e32 v32, v0
	v_mov_b32_e32 v33, v0
	v_mov_b32_e32 v34, v0
	v_mov_b32_e32 v35, v0
	v_mov_b32_e32 v40, v0
	v_mov_b32_e32 v41, v0
	v_mov_b32_e32 v42, v0
	v_mov_b32_e32 v43, v0
	v_mov_b32_e32 v48, v0
	v_mov_b32_e32 v49, v0
	v_mov_b32_e32 v50, v0
	v_mov_b32_e32 v51, v0
	v_mov_b32_e32 v52, v0
	v_mov_b32_e32 v53, v0
	v_mov_b32_e32 v54, v0
	v_mov_b32_e32 v55, v0
	v_mov_b32_e32 v56, v0
	v_mov_b32_e32 v57, v0
	v_mov_b32_e32 v58, v0
	v_mov_b32_e32 v59, v0
	v_mov_b32_e32 v60, v0
	v_mov_b32_e32 v61, v0
	v_mov_b32_e32 v62, v0
	v_mov_b32_e32 v63, v0
	v_mov_b32_e32 v64, v0
	v_mov_b32_e32 v65, v0
	v_mov_b32_e32 v66, v0
	v_mov_b32_e32 v67, v0
	v_mov_b32_e32 v68, v0
	v_mov_b32_e32 v69, v0
	v_mov_b32_e32 v70, v0
	v_mov_b32_e32 v71, v0
	v_mov_b32_e32 v72, v0
	v_mov_b32_e32 v73, v0
	v_mov_b32_e32 v74, v0
	v_mov_b32_e32 v75, v0
	v_mov_b32_e32 v76, v0
	v_mov_b32_e32 v77, v0
	v_mov_b32_e32 v78, v0
	v_mov_b32_e32 v79, v0
	v_mov_b32_e32 v84, v0
	v_mov_b32_e32 v85, v0
	v_mov_b32_e32 v86, v0
	v_mov_b32_e32 v87, v0
	v_mov_b32_e32 v92, v0
	v_mov_b32_e32 v93, v0
	v_mov_b32_e32 v94, v0
	v_mov_b32_e32 v95, v0
	v_mov_b32_e32 v100, v0
	v_mov_b32_e32 v101, v0
	v_mov_b32_e32 v102, v0
	v_mov_b32_e32 v103, v0
	v_mov_b32_e32 v108, v0
	v_mov_b32_e32 v109, v0
	v_mov_b32_e32 v110, v0
	v_mov_b32_e32 v111, v0
	v_mov_b32_e32 v80, v0
	v_mov_b32_e32 v81, v0
	v_mov_b32_e32 v82, v0
	v_mov_b32_e32 v83, v0
	v_mov_b32_e32 v88, v0
	v_mov_b32_e32 v89, v0
	v_mov_b32_e32 v90, v0
	v_mov_b32_e32 v91, v0
	v_mov_b32_e32 v96, v0
	v_mov_b32_e32 v97, v0
	v_mov_b32_e32 v98, v0
	v_mov_b32_e32 v99, v0
	v_mov_b32_e32 v104, v0
	v_mov_b32_e32 v105, v0
	v_mov_b32_e32 v106, v0
	v_mov_b32_e32 v107, v0
	v_mov_b32_e32 v112, v0
	v_mov_b32_e32 v113, v0
	v_mov_b32_e32 v114, v0
	v_mov_b32_e32 v115, v0
	v_mov_b32_e32 v116, v0
	v_mov_b32_e32 v117, v0
	v_mov_b32_e32 v118, v0
	v_mov_b32_e32 v119, v0
	v_mov_b32_e32 v120, v0
	v_mov_b32_e32 v121, v0
	v_mov_b32_e32 v122, v0
	v_mov_b32_e32 v123, v0
	v_mov_b32_e32 v124, v0
	v_mov_b32_e32 v125, v0
	v_mov_b32_e32 v126, v0
	v_mov_b32_e32 v127, v0
	.p2align	6

; #define PG8_STAGE(bufoff, gbase, voff) do { _Pragma("unroll") for (int _i = 0; _i < 2; ++_i) \
;         __builtin_amdgcn_global_load_lds((const unsigned*)((const char*)(gbase) + (voff)[_i]), (LAS unsigned*)(lds + (bufoff) + ldsw + _i * 8192), 16, 0, 0); } while (0)
; #define PG8_WAIT_V(n) asm volatile("s_waitcnt vmcnt(" #n ")" ::: "memory")
; #define PG8_BAR __builtin_amdgcn_s_barrier()
; template <class Epi, bool ALIGN_EPI = PG8_ALIGN>
; __device__ __forceinline__ void gemm_phase(LAS unsigned char* lds, const Gemm g, const StaticOrder& S, const Epi& E) {
;     ...
;     const char* cA = (const char*)g.A + (size_t)cur.pm * tstepA; const char* cB = (const char*)g.Bt + (size_t)cur.pn * tstepB;
;     PG8_STAGE(PG8_SB(0, 0), cB, voffB); PG8_STAGE(PG8_SB(0, 1), cB + hstepB, voffB); PG8_STAGE(PG8_SA(0, 0), cA, voffA); PG8_STAGE(PG8_SA(0, 1), cA + hstepA, voffA);
;     if (wr == 1) PG8_BAR;
;     PG8_WAIT_V(2); PG8_BAR;
;     PG8_STAGE(PG8_SB(1, 0), cB + kstep, voffB); PG8_STAGE(PG8_SA(1, 0), cA + kstep, voffA); PG8_STAGE(PG8_SB(1, 1), cB + hstepB + kstep, voffB);
;     PG8_WAIT_V(6); PG8_BAR;
;     for (;;) {
;         const bool has_next = S.next(ui + 1, nxt);
;         const char* nA = has_next ? (const char*)g.A + (size_t)nxt.pm * tstepA : cA; const char* nB = has_next ? (const char*)g.Bt + (size_t)nxt.pn * tstepB : cB;
;         for (int t = 0; t < nt; t += 2) {
;             const bool last = (t == nt - 2);
;             const char* a1 = cA + (size_t)(t + 1) * kstep;
;             const char* a2 = last ? nA : cA + (size_t)(t + 2) * kstep; const char* b2 = last ? nB : cB + (size_t)(t + 2) * kstep;
.LBB0_456:
	s_ashr_i32 s17, s16, 31
	s_lshl_b64 s[36:37], s[16:17], 20
	s_add_u32 s36, s58, s36
	v_mov_b32_e32 v123, 0
	s_addc_u32 s37, s59, s37
	s_andn2_b64 vcc, exec, s[12:13]
	v_mov_b32_e32 v122, v123
	v_mov_b32_e32 v121, v123
	v_mov_b32_e32 v120, v123
	v_mov_b32_e32 v127, v123
	v_mov_b32_e32 v126, v123
	v_mov_b32_e32 v125, v123
	v_mov_b32_e32 v124, v123
	v_mov_b32_e32 v111, v123
	v_mov_b32_e32 v110, v123
	v_mov_b32_e32 v109, v123
	v_mov_b32_e32 v108, v123
	v_mov_b32_e32 v107, v123
	v_mov_b32_e32 v106, v123
	v_mov_b32_e32 v105, v123
	v_mov_b32_e32 v104, v123
	v_mov_b32_e32 v95, v123
	v_mov_b32_e32 v94, v123
	v_mov_b32_e32 v93, v123
	v_mov_b32_e32 v92, v123
	v_mov_b32_e32 v91, v123
	v_mov_b32_e32 v90, v123
	v_mov_b32_e32 v89, v123
	v_mov_b32_e32 v88, v123
	v_mov_b32_e32 v79, v123
	v_mov_b32_e32 v78, v123
	v_mov_b32_e32 v77, v123
	v_mov_b32_e32 v76, v123
	v_mov_b32_e32 v75, v123
	v_mov_b32_e32 v74, v123
	v_mov_b32_e32 v73, v123
	v_mov_b32_e32 v72, v123
	v_mov_b32_e32 v119, v123
	v_mov_b32_e32 v118, v123
	v_mov_b32_e32 v117, v123
	v_mov_b32_e32 v116, v123
	v_mov_b32_e32 v115, v123
	v_mov_b32_e32 v114, v123
	v_mov_b32_e32 v113, v123
	v_mov_b32_e32 v112, v123
	v_mov_b32_e32 v103, v123
	v_mov_b32_e32 v102, v123
	v_mov_b32_e32 v101, v123
	v_mov_b32_e32 v100, v123
	v_mov_b32_e32 v99, v123
	v_mov_b32_e32 v98, v123
	v_mov_b32_e32 v97, v123
	v_mov_b32_e32 v96, v123
	v_mov_b32_e32 v87, v123
	v_mov_b32_e32 v86, v123
	v_mov_b32_e32 v85, v123
	v_mov_b32_e32 v84, v123
	v_mov_b32_e32 v83, v123
	v_mov_b32_e32 v82, v123
	v_mov_b32_e32 v81, v123
	v_mov_b32_e32 v80, v123
	v_mov_b32_e32 v71, v123
	v_mov_b32_e32 v70, v123
	v_mov_b32_e32 v69, v123
	v_mov_b32_e32 v68, v123
	v_mov_b32_e32 v67, v123
	v_mov_b32_e32 v66, v123
	v_mov_b32_e32 v65, v123
	v_mov_b32_e32 v64, v123
	v_mov_b32_e32 v63, v123
	v_mov_b32_e32 v62, v123
	v_mov_b32_e32 v61, v123
	v_mov_b32_e32 v60, v123
	v_mov_b32_e32 v59, v123
	v_mov_b32_e32 v58, v123
	v_mov_b32_e32 v57, v123
	v_mov_b32_e32 v56, v123
	v_mov_b32_e32 v47, v123
	v_mov_b32_e32 v46, v123
	v_mov_b32_e32 v45, v123
	v_mov_b32_e32 v44, v123
	v_mov_b32_e32 v43, v123
	v_mov_b32_e32 v42, v123
	v_mov_b32_e32 v41, v123
	v_mov_b32_e32 v40, v123
	v_mov_b32_e32 v31, v123
	v_mov_b32_e32 v30, v123
	v_mov_b32_e32 v29, v123
	v_mov_b32_e32 v28, v123
	v_mov_b32_e32 v27, v123
	v_mov_b32_e32 v26, v123
	v_mov_b32_e32 v25, v123
	v_mov_b32_e32 v24, v123
	v_mov_b32_e32 v15, v123
	v_mov_b32_e32 v14, v123
	v_mov_b32_e32 v13, v123
	v_mov_b32_e32 v12, v123
	v_mov_b32_e32 v11, v123
	v_mov_b32_e32 v10, v123
	v_mov_b32_e32 v9, v123
	v_mov_b32_e32 v8, v123
	v_mov_b32_e32 v55, v123
	v_mov_b32_e32 v54, v123
	v_mov_b32_e32 v53, v123
	v_mov_b32_e32 v52, v123
	v_mov_b32_e32 v51, v123
	v_mov_b32_e32 v50, v123
	v_mov_b32_e32 v49, v123
	v_mov_b32_e32 v48, v123
	v_mov_b32_e32 v39, v123
	v_mov_b32_e32 v38, v123
	v_mov_b32_e32 v37, v123
	v_mov_b32_e32 v36, v123
	v_mov_b32_e32 v35, v123
	v_mov_b32_e32 v34, v123
	v_mov_b32_e32 v33, v123
	v_mov_b32_e32 v32, v123
	v_mov_b32_e32 v23, v123
	v_mov_b32_e32 v22, v123
	v_mov_b32_e32 v21, v123
	v_mov_b32_e32 v20, v123
	v_mov_b32_e32 v19, v123
	v_mov_b32_e32 v18, v123
	v_mov_b32_e32 v17, v123
	v_mov_b32_e32 v16, v123
	v_mov_b32_e32 v7, v123
	v_mov_b32_e32 v6, v123
	v_mov_b32_e32 v5, v123
	v_mov_b32_e32 v4, v123
	v_mov_b32_e32 v3, v123
	v_mov_b32_e32 v2, v123
	v_mov_b32_e32 v1, v123
	v_mov_b32_e32 v0, v123
	s_cbranch_vccnz .LBB0_459
	s_and_b64 s[4:5], s[4:5], exec
	s_cselect_b32 s17, s37, s41
	s_cselect_b32 s50, s36, s40
	s_add_u32 s4, s40, 0x80080
	s_addc_u32 s5, s41, 0
	s_add_u32 s40, s38, 0x100
	v_mov_b32_e32 v0, 0
	s_addc_u32 s41, s39, 0
	s_mov_b32 s38, 0
	v_mov_b32_e32 v1, v0
	v_mov_b32_e32 v2, v0
	v_mov_b32_e32 v3, v0
	v_mov_b32_e32 v4, v0
	v_mov_b32_e32 v5, v0
	v_mov_b32_e32 v6, v0
	v_mov_b32_e32 v7, v0
	v_mov_b32_e32 v16, v0
	v_mov_b32_e32 v17, v0
	v_mov_b32_e32 v18, v0
	v_mov_b32_e32 v19, v0
	v_mov_b32_e32 v20, v0
	v_mov_b32_e32 v21, v0
	v_mov_b32_e32 v22, v0
	v_mov_b32_e32 v23, v0
	v_mov_b32_e32 v32, v0
	v_mov_b32_e32 v33, v0
	v_mov_b32_e32 v34, v0
	v_mov_b32_e32 v35, v0
	v_mov_b32_e32 v36, v0
	v_mov_b32_e32 v37, v0
	v_mov_b32_e32 v38, v0
	v_mov_b32_e32 v39, v0
	v_mov_b32_e32 v48, v0
	v_mov_b32_e32 v49, v0
	v_mov_b32_e32 v50, v0
	v_mov_b32_e32 v51, v0
	v_mov_b32_e32 v52, v0
	v_mov_b32_e32 v53, v0
	v_mov_b32_e32 v54, v0
	v_mov_b32_e32 v55, v0
	v_mov_b32_e32 v8, v0
	v_mov_b32_e32 v9, v0
	v_mov_b32_e32 v10, v0
	v_mov_b32_e32 v11, v0
	v_mov_b32_e32 v12, v0
	v_mov_b32_e32 v13, v0
	v_mov_b32_e32 v14, v0
	v_mov_b32_e32 v15, v0
	v_mov_b32_e32 v24, v0
	v_mov_b32_e32 v25, v0
	v_mov_b32_e32 v26, v0
	v_mov_b32_e32 v27, v0
	v_mov_b32_e32 v28, v0
	v_mov_b32_e32 v29, v0
	v_mov_b32_e32 v30, v0
	v_mov_b32_e32 v31, v0
	v_mov_b32_e32 v40, v0
	v_mov_b32_e32 v41, v0
	v_mov_b32_e32 v42, v0
	v_mov_b32_e32 v43, v0
	v_mov_b32_e32 v44, v0
	v_mov_b32_e32 v45, v0
	v_mov_b32_e32 v46, v0
	v_mov_b32_e32 v47, v0
	v_mov_b32_e32 v56, v0
	v_mov_b32_e32 v57, v0
	v_mov_b32_e32 v58, v0
	v_mov_b32_e32 v59, v0
	v_mov_b32_e32 v60, v0
	v_mov_b32_e32 v61, v0
	v_mov_b32_e32 v62, v0
	v_mov_b32_e32 v63, v0
	v_mov_b32_e32 v64, v0
	v_mov_b32_e32 v65, v0
	v_mov_b32_e32 v66, v0
	v_mov_b32_e32 v67, v0
	v_mov_b32_e32 v68, v0
	v_mov_b32_e32 v69, v0
	v_mov_b32_e32 v70, v0
	v_mov_b32_e32 v71, v0
	v_mov_b32_e32 v80, v0
	v_mov_b32_e32 v81, v0
	v_mov_b32_e32 v82, v0
	v_mov_b32_e32 v83, v0
	v_mov_b32_e32 v84, v0
	v_mov_b32_e32 v85, v0
	v_mov_b32_e32 v86, v0
	v_mov_b32_e32 v87, v0
	v_mov_b32_e32 v96, v0
	v_mov_b32_e32 v97, v0
	v_mov_b32_e32 v98, v0
	v_mov_b32_e32 v99, v0
	v_mov_b32_e32 v100, v0
	v_mov_b32_e32 v101, v0
	v_mov_b32_e32 v102, v0
	v_mov_b32_e32 v103, v0
	v_mov_b32_e32 v112, v0
	v_mov_b32_e32 v113, v0
	v_mov_b32_e32 v114, v0
	v_mov_b32_e32 v115, v0
	v_mov_b32_e32 v116, v0
	v_mov_b32_e32 v117, v0
	v_mov_b32_e32 v118, v0
	v_mov_b32_e32 v119, v0
	v_mov_b32_e32 v72, v0
	v_mov_b32_e32 v73, v0
	v_mov_b32_e32 v74, v0
	v_mov_b32_e32 v75, v0
	v_mov_b32_e32 v76, v0
	v_mov_b32_e32 v77, v0
	v_mov_b32_e32 v78, v0
	v_mov_b32_e32 v79, v0
	v_mov_b32_e32 v88, v0
	v_mov_b32_e32 v89, v0
	v_mov_b32_e32 v90, v0
	v_mov_b32_e32 v91, v0
	v_mov_b32_e32 v92, v0
	v_mov_b32_e32 v93, v0
	v_mov_b32_e32 v94, v0
	v_mov_b32_e32 v95, v0
	v_mov_b32_e32 v104, v0
	v_mov_b32_e32 v105, v0
	v_mov_b32_e32 v106, v0
	v_mov_b32_e32 v107, v0
	v_mov_b32_e32 v108, v0
	v_mov_b32_e32 v109, v0
	v_mov_b32_e32 v110, v0
	v_mov_b32_e32 v111, v0
	v_mov_b32_e32 v124, v0
	v_mov_b32_e32 v125, v0
	v_mov_b32_e32 v126, v0
	v_mov_b32_e32 v127, v0
	v_mov_b32_e32 v120, v0
	v_mov_b32_e32 v121, v0
	v_mov_b32_e32 v122, v0
	v_mov_b32_e32 v123, v0
	.p2align	6

; #define PG8_STAGE(bufoff, gbase, voff) do { _Pragma("unroll") for (int _i = 0; _i < 2; ++_i) \
;         __builtin_amdgcn_global_load_lds((const unsigned*)((const char*)(gbase) + (voff)[_i]), (LAS unsigned*)(lds + (bufoff) + ldsw + _i * 8192), 16, 0, 0); } while (0)
; #define PG8_WAIT_V(n) asm volatile("s_waitcnt vmcnt(" #n ")" ::: "memory")
; #define PG8_BAR __builtin_amdgcn_s_barrier()
; template <class Epi, bool ALIGN_EPI = PG8_ALIGN>
; __device__ __forceinline__ void gemm_phase(LAS unsigned char* lds, const Gemm g, const StaticOrder& S, const Epi& E) {
;     ...
;     const char* cA = (const char*)g.A + (size_t)cur.pm * tstepA; const char* cB = (const char*)g.Bt + (size_t)cur.pn * tstepB;
;     PG8_STAGE(PG8_SB(0, 0), cB, voffB); PG8_STAGE(PG8_SB(0, 1), cB + hstepB, voffB); PG8_STAGE(PG8_SA(0, 0), cA, voffA); PG8_STAGE(PG8_SA(0, 1), cA + hstepA, voffA);
;     if (wr == 1) PG8_BAR;
;     PG8_WAIT_V(2); PG8_BAR;
;     PG8_STAGE(PG8_SB(1, 0), cB + kstep, voffB); PG8_STAGE(PG8_SA(1, 0), cA + kstep, voffA); PG8_STAGE(PG8_SB(1, 1), cB + hstepB + kstep, voffB);
;     PG8_WAIT_V(6); PG8_BAR;
;     for (;;) {
;         const bool has_next = S.next(ui + 1, nxt);
;         const char* nA = has_next ? (const char*)g.A + (size_t)nxt.pm * tstepA : cA; const char* nB = has_next ? (const char*)g.Bt + (size_t)nxt.pn * tstepB : cB;
;         for (int t = 0; t < nt; t += 2) {
;             const bool last = (t == nt - 2);
;             const char* a1 = cA + (size_t)(t + 1) * kstep;
;             const char* a2 = last ? nA : cA + (size_t)(t + 2) * kstep; const char* b2 = last ? nB : cB + (size_t)(t + 2) * kstep;
.LBB0_479:
	s_ashr_i32 s17, s16, 31
	s_lshl_b64 s[36:37], s[16:17], 17
	s_add_u32 s36, s18, s36
	v_mov_b32_e32 v123, 0
	s_addc_u32 s37, s29, s37
	s_andn2_b64 vcc, exec, s[12:13]
	v_mov_b32_e32 v122, v123
	v_mov_b32_e32 v121, v123
	v_mov_b32_e32 v120, v123
	v_mov_b32_e32 v127, v123
	v_mov_b32_e32 v126, v123
	v_mov_b32_e32 v125, v123
	v_mov_b32_e32 v124, v123
	v_mov_b32_e32 v111, v123
	v_mov_b32_e32 v110, v123
	v_mov_b32_e32 v109, v123
	v_mov_b32_e32 v108, v123
	v_mov_b32_e32 v107, v123
	v_mov_b32_e32 v106, v123
	v_mov_b32_e32 v105, v123
	v_mov_b32_e32 v104, v123
	v_mov_b32_e32 v95, v123
	v_mov_b32_e32 v94, v123
	v_mov_b32_e32 v93, v123
	v_mov_b32_e32 v92, v123
	v_mov_b32_e32 v91, v123
	v_mov_b32_e32 v90, v123
	v_mov_b32_e32 v89, v123
	v_mov_b32_e32 v88, v123
	v_mov_b32_e32 v79, v123
	v_mov_b32_e32 v78, v123
	v_mov_b32_e32 v77, v123
	v_mov_b32_e32 v76, v123
	v_mov_b32_e32 v75, v123
	v_mov_b32_e32 v74, v123
	v_mov_b32_e32 v73, v123
	v_mov_b32_e32 v72, v123
	v_mov_b32_e32 v119, v123
	v_mov_b32_e32 v118, v123
	v_mov_b32_e32 v117, v123
	v_mov_b32_e32 v116, v123
	v_mov_b32_e32 v115, v123
	v_mov_b32_e32 v114, v123
	v_mov_b32_e32 v113, v123
	v_mov_b32_e32 v112, v123
	v_mov_b32_e32 v103, v123
	v_mov_b32_e32 v102, v123
	v_mov_b32_e32 v101, v123
	v_mov_b32_e32 v100, v123
	v_mov_b32_e32 v99, v123
	v_mov_b32_e32 v98, v123
	v_mov_b32_e32 v97, v123
	v_mov_b32_e32 v96, v123
	v_mov_b32_e32 v87, v123
	v_mov_b32_e32 v86, v123
	v_mov_b32_e32 v85, v123
	v_mov_b32_e32 v84, v123
	v_mov_b32_e32 v83, v123
	v_mov_b32_e32 v82, v123
	v_mov_b32_e32 v81, v123
	v_mov_b32_e32 v80, v123
	v_mov_b32_e32 v71, v123
	v_mov_b32_e32 v70, v123
	v_mov_b32_e32 v69, v123
	v_mov_b32_e32 v68, v123
	v_mov_b32_e32 v67, v123
	v_mov_b32_e32 v66, v123
	v_mov_b32_e32 v65, v123
	v_mov_b32_e32 v64, v123
	v_mov_b32_e32 v63, v123
	v_mov_b32_e32 v62, v123
	v_mov_b32_e32 v61, v123
	v_mov_b32_e32 v60, v123
	v_mov_b32_e32 v59, v123
	v_mov_b32_e32 v58, v123
	v_mov_b32_e32 v57, v123
	v_mov_b32_e32 v56, v123
	v_mov_b32_e32 v47, v123
	v_mov_b32_e32 v46, v123
	v_mov_b32_e32 v45, v123
	v_mov_b32_e32 v44, v123
	v_mov_b32_e32 v43, v123
	v_mov_b32_e32 v42, v123
	v_mov_b32_e32 v41, v123
	v_mov_b32_e32 v40, v123
	v_mov_b32_e32 v31, v123
	v_mov_b32_e32 v30, v123
	v_mov_b32_e32 v29, v123
	v_mov_b32_e32 v28, v123
	v_mov_b32_e32 v27, v123
	v_mov_b32_e32 v26, v123
	v_mov_b32_e32 v25, v123
	v_mov_b32_e32 v24, v123
	v_mov_b32_e32 v15, v123
	v_mov_b32_e32 v14, v123
	v_mov_b32_e32 v13, v123
	v_mov_b32_e32 v12, v123
	v_mov_b32_e32 v11, v123
	v_mov_b32_e32 v10, v123
	v_mov_b32_e32 v9, v123
	v_mov_b32_e32 v8, v123
	v_mov_b32_e32 v55, v123
	v_mov_b32_e32 v54, v123
	v_mov_b32_e32 v53, v123
	v_mov_b32_e32 v52, v123
	v_mov_b32_e32 v51, v123
	v_mov_b32_e32 v50, v123
	v_mov_b32_e32 v49, v123
	v_mov_b32_e32 v48, v123
	v_mov_b32_e32 v39, v123
	v_mov_b32_e32 v38, v123
	v_mov_b32_e32 v37, v123
	v_mov_b32_e32 v36, v123
	v_mov_b32_e32 v35, v123
	v_mov_b32_e32 v34, v123
	v_mov_b32_e32 v33, v123
	v_mov_b32_e32 v32, v123
	v_mov_b32_e32 v23, v123
	v_mov_b32_e32 v22, v123
	v_mov_b32_e32 v21, v123
	v_mov_b32_e32 v20, v123
	v_mov_b32_e32 v19, v123
	v_mov_b32_e32 v18, v123
	v_mov_b32_e32 v17, v123
	v_mov_b32_e32 v16, v123
	v_mov_b32_e32 v7, v123
	v_mov_b32_e32 v6, v123
	v_mov_b32_e32 v5, v123
	v_mov_b32_e32 v4, v123
	v_mov_b32_e32 v3, v123
	v_mov_b32_e32 v2, v123
	v_mov_b32_e32 v1, v123
	v_mov_b32_e32 v0, v123
	s_cbranch_vccnz .LBB0_482
	s_and_b64 s[4:5], s[4:5], exec
	s_cselect_b32 s17, s37, s41
	s_cselect_b32 s52, s36, s40
	s_add_u32 s4, s40, 0x10080
	s_addc_u32 s5, s41, 0
	s_add_u32 s40, s38, 0x100
	v_mov_b32_e32 v0, 0
	s_addc_u32 s41, s39, 0
	s_mov_b32 s38, 0
	v_mov_b32_e32 v1, v0
	v_mov_b32_e32 v2, v0
	v_mov_b32_e32 v3, v0
	v_mov_b32_e32 v4, v0
	v_mov_b32_e32 v5, v0
	v_mov_b32_e32 v6, v0
	v_mov_b32_e32 v7, v0
	v_mov_b32_e32 v16, v0
	v_mov_b32_e32 v17, v0
	v_mov_b32_e32 v18, v0
	v_mov_b32_e32 v19, v0
	v_mov_b32_e32 v20, v0
	v_mov_b32_e32 v21, v0
	v_mov_b32_e32 v22, v0
	v_mov_b32_e32 v23, v0
	v_mov_b32_e32 v32, v0
	v_mov_b32_e32 v33, v0
	v_mov_b32_e32 v34, v0
	v_mov_b32_e32 v35, v0
	v_mov_b32_e32 v36, v0
	v_mov_b32_e32 v37, v0
	v_mov_b32_e32 v38, v0
	v_mov_b32_e32 v39, v0
	v_mov_b32_e32 v48, v0
	v_mov_b32_e32 v49, v0
	v_mov_b32_e32 v50, v0
	v_mov_b32_e32 v51, v0
	v_mov_b32_e32 v52, v0
	v_mov_b32_e32 v53, v0
	v_mov_b32_e32 v54, v0
	v_mov_b32_e32 v55, v0
	v_mov_b32_e32 v8, v0
	v_mov_b32_e32 v9, v0
	v_mov_b32_e32 v10, v0
	v_mov_b32_e32 v11, v0
	v_mov_b32_e32 v12, v0
	v_mov_b32_e32 v13, v0
	v_mov_b32_e32 v14, v0
	v_mov_b32_e32 v15, v0
	v_mov_b32_e32 v24, v0
	v_mov_b32_e32 v25, v0
	v_mov_b32_e32 v26, v0
	v_mov_b32_e32 v27, v0
	v_mov_b32_e32 v28, v0
	v_mov_b32_e32 v29, v0
	v_mov_b32_e32 v30, v0
	v_mov_b32_e32 v31, v0
	v_mov_b32_e32 v40, v0
	v_mov_b32_e32 v41, v0
	v_mov_b32_e32 v42, v0
	v_mov_b32_e32 v43, v0
	v_mov_b32_e32 v44, v0
	v_mov_b32_e32 v45, v0
	v_mov_b32_e32 v46, v0
	v_mov_b32_e32 v47, v0
	v_mov_b32_e32 v56, v0
	v_mov_b32_e32 v57, v0
	v_mov_b32_e32 v58, v0
	v_mov_b32_e32 v59, v0
	v_mov_b32_e32 v60, v0
	v_mov_b32_e32 v61, v0
	v_mov_b32_e32 v62, v0
	v_mov_b32_e32 v63, v0
	v_mov_b32_e32 v64, v0
	v_mov_b32_e32 v65, v0
	v_mov_b32_e32 v66, v0
	v_mov_b32_e32 v67, v0
	v_mov_b32_e32 v68, v0
	v_mov_b32_e32 v69, v0
	v_mov_b32_e32 v70, v0
	v_mov_b32_e32 v71, v0
	v_mov_b32_e32 v80, v0
	v_mov_b32_e32 v81, v0
	v_mov_b32_e32 v82, v0
	v_mov_b32_e32 v83, v0
	v_mov_b32_e32 v84, v0
	v_mov_b32_e32 v85, v0
	v_mov_b32_e32 v86, v0
	v_mov_b32_e32 v87, v0
	v_mov_b32_e32 v96, v0
	v_mov_b32_e32 v97, v0
	v_mov_b32_e32 v98, v0
	v_mov_b32_e32 v99, v0
	v_mov_b32_e32 v100, v0
	v_mov_b32_e32 v101, v0
	v_mov_b32_e32 v102, v0
	v_mov_b32_e32 v103, v0
	v_mov_b32_e32 v112, v0
	v_mov_b32_e32 v113, v0
	v_mov_b32_e32 v114, v0
	v_mov_b32_e32 v115, v0
	v_mov_b32_e32 v116, v0
	v_mov_b32_e32 v117, v0
	v_mov_b32_e32 v118, v0
	v_mov_b32_e32 v119, v0
	v_mov_b32_e32 v72, v0
	v_mov_b32_e32 v73, v0
	v_mov_b32_e32 v74, v0
	v_mov_b32_e32 v75, v0
	v_mov_b32_e32 v76, v0
	v_mov_b32_e32 v77, v0
	v_mov_b32_e32 v78, v0
	v_mov_b32_e32 v79, v0
	v_mov_b32_e32 v88, v0
	v_mov_b32_e32 v89, v0
	v_mov_b32_e32 v90, v0
	v_mov_b32_e32 v91, v0
	v_mov_b32_e32 v92, v0
	v_mov_b32_e32 v93, v0
	v_mov_b32_e32 v94, v0
	v_mov_b32_e32 v95, v0
	v_mov_b32_e32 v104, v0
	v_mov_b32_e32 v105, v0
	v_mov_b32_e32 v106, v0
	v_mov_b32_e32 v107, v0
	v_mov_b32_e32 v108, v0
	v_mov_b32_e32 v109, v0
	v_mov_b32_e32 v110, v0
	v_mov_b32_e32 v111, v0
	v_mov_b32_e32 v124, v0
	v_mov_b32_e32 v125, v0
	v_mov_b32_e32 v126, v0
	v_mov_b32_e32 v127, v0
	v_mov_b32_e32 v120, v0
	v_mov_b32_e32 v121, v0
	v_mov_b32_e32 v122, v0
	v_mov_b32_e32 v123, v0
	.p2align	6

; #define PG8_STAGE(bufoff, gbase, voff) do { _Pragma("unroll") for (int _i = 0; _i < 2; ++_i) \
;         __builtin_amdgcn_global_load_lds((const unsigned*)((const char*)(gbase) + (voff)[_i]), (LAS unsigned*)(lds + (bufoff) + ldsw + _i * 8192), 16, 0, 0); } while (0)
; #define PG8_WAIT_V(n) asm volatile("s_waitcnt vmcnt(" #n ")" ::: "memory")
; #define PG8_BAR __builtin_amdgcn_s_barrier()
; template <class Epi, bool ALIGN_EPI = PG8_ALIGN>
; __device__ __forceinline__ void gemm_phase(LAS unsigned char* lds, const Gemm g, const StaticOrder& S, const Epi& E) {
;     ...
;     f32x4 acc[2][2][4][2];
; #pragma unroll
;     for (int a = 0; a < 2; ++a)
; #pragma unroll
;         for (int b = 0; b < 2; ++b)
; #pragma unroll
;             for (int m = 0; m < 4; ++m)
; #pragma unroll
;                 for (int n = 0; n < 2; ++n) acc[a][b][m][n] = (f32x4){0.f, 0.f, 0.f, 0.f};
;     bf16x8 At[4][2], B0[2][2], B1[2][2];
;     const char* cA = (const char*)g.A + (size_t)cur.pm * tstepA; const char* cB = (const char*)g.Bt + (size_t)cur.pn * tstepB;
;     PG8_STAGE(PG8_SB(0, 0), cB, voffB); PG8_STAGE(PG8_SB(0, 1), cB + hstepB, voffB); PG8_STAGE(PG8_SA(0, 0), cA, voffA); PG8_STAGE(PG8_SA(0, 1), cA + hstepA, voffA);
;     if (wr == 1) PG8_BAR;
;     PG8_WAIT_V(2); PG8_BAR;
;     PG8_STAGE(PG8_SB(1, 0), cB + kstep, voffB); PG8_STAGE(PG8_SA(1, 0), cA + kstep, voffA); PG8_STAGE(PG8_SB(1, 1), cB + hstepB + kstep, voffB);
;     PG8_WAIT_V(6); PG8_BAR;
;     for (;;) {
;         const bool has_next = S.next(ui + 1, nxt);
;         const char* nA = has_next ? (const char*)g.A + (size_t)nxt.pm * tstepA : cA; const char* nB = has_next ? (const char*)g.Bt + (size_t)nxt.pn * tstepB : cB;
;         for (int t = 0; t < nt; t += 2) {
.LBB0_640:
	v_mov_b32_e32 v123, 0
	s_andn2_b64 vcc, exec, s[12:13]
	v_mov_b32_e32 v122, v123
	v_mov_b32_e32 v121, v123
	v_mov_b32_e32 v120, v123
	v_mov_b32_e32 v127, v123
	v_mov_b32_e32 v126, v123
	v_mov_b32_e32 v125, v123
	v_mov_b32_e32 v124, v123
	v_mov_b32_e32 v111, v123
	v_mov_b32_e32 v110, v123
	v_mov_b32_e32 v109, v123
	v_mov_b32_e32 v108, v123
	v_mov_b32_e32 v107, v123
	v_mov_b32_e32 v106, v123
	v_mov_b32_e32 v105, v123
	v_mov_b32_e32 v104, v123
	v_mov_b32_e32 v95, v123
	v_mov_b32_e32 v94, v123
	v_mov_b32_e32 v93, v123
	v_mov_b32_e32 v92, v123
	v_mov_b32_e32 v91, v123
	v_mov_b32_e32 v90, v123
	v_mov_b32_e32 v89, v123
	v_mov_b32_e32 v88, v123
	v_mov_b32_e32 v79, v123
	v_mov_b32_e32 v78, v123
	v_mov_b32_e32 v77, v123
	v_mov_b32_e32 v76, v123
	v_mov_b32_e32 v75, v123
	v_mov_b32_e32 v74, v123
	v_mov_b32_e32 v73, v123
	v_mov_b32_e32 v72, v123
	v_mov_b32_e32 v119, v123
	v_mov_b32_e32 v118, v123
	v_mov_b32_e32 v117, v123
	v_mov_b32_e32 v116, v123
	v_mov_b32_e32 v115, v123
	v_mov_b32_e32 v114, v123
	v_mov_b32_e32 v113, v123
	v_mov_b32_e32 v112, v123
	v_mov_b32_e32 v103, v123
	v_mov_b32_e32 v102, v123
	v_mov_b32_e32 v101, v123
	v_mov_b32_e32 v100, v123
	v_mov_b32_e32 v99, v123
	v_mov_b32_e32 v98, v123
	v_mov_b32_e32 v97, v123
	v_mov_b32_e32 v96, v123
	v_mov_b32_e32 v87, v123
	v_mov_b32_e32 v86, v123
	v_mov_b32_e32 v85, v123
	v_mov_b32_e32 v84, v123
	v_mov_b32_e32 v83, v123
	v_mov_b32_e32 v82, v123
	v_mov_b32_e32 v81, v123
	v_mov_b32_e32 v80, v123
	v_mov_b32_e32 v71, v123
	v_mov_b32_e32 v70, v123
	v_mov_b32_e32 v69, v123
	v_mov_b32_e32 v68, v123
	v_mov_b32_e32 v67, v123
	v_mov_b32_e32 v66, v123
	v_mov_b32_e32 v65, v123
	v_mov_b32_e32 v64, v123
	v_mov_b32_e32 v63, v123
	v_mov_b32_e32 v62, v123
	v_mov_b32_e32 v61, v123
	v_mov_b32_e32 v60, v123
	v_mov_b32_e32 v59, v123
	v_mov_b32_e32 v58, v123
	v_mov_b32_e32 v57, v123
	v_mov_b32_e32 v56, v123
	v_mov_b32_e32 v47, v123
	v_mov_b32_e32 v46, v123
	v_mov_b32_e32 v45, v123
	v_mov_b32_e32 v44, v123
	v_mov_b32_e32 v43, v123
	v_mov_b32_e32 v42, v123
	v_mov_b32_e32 v41, v123
	v_mov_b32_e32 v40, v123
	v_mov_b32_e32 v31, v123
	v_mov_b32_e32 v30, v123
	v_mov_b32_e32 v29, v123
	v_mov_b32_e32 v28, v123
	v_mov_b32_e32 v27, v123
	v_mov_b32_e32 v26, v123
	v_mov_b32_e32 v25, v123
	v_mov_b32_e32 v24, v123
	v_mov_b32_e32 v15, v123
	v_mov_b32_e32 v14, v123
	v_mov_b32_e32 v13, v123
	v_mov_b32_e32 v12, v123
	v_mov_b32_e32 v11, v123
	v_mov_b32_e32 v10, v123
	v_mov_b32_e32 v9, v123
	v_mov_b32_e32 v8, v123
	v_mov_b32_e32 v55, v123
	v_mov_b32_e32 v54, v123
	v_mov_b32_e32 v53, v123
	v_mov_b32_e32 v52, v123
	v_mov_b32_e32 v51, v123
	v_mov_b32_e32 v50, v123
	v_mov_b32_e32 v49, v123
	v_mov_b32_e32 v48, v123
	v_mov_b32_e32 v39, v123
	v_mov_b32_e32 v38, v123
	v_mov_b32_e32 v37, v123
	v_mov_b32_e32 v36, v123
	v_mov_b32_e32 v35, v123
	v_mov_b32_e32 v34, v123
	v_mov_b32_e32 v33, v123
	v_mov_b32_e32 v32, v123
	v_mov_b32_e32 v23, v123
	v_mov_b32_e32 v22, v123
	v_mov_b32_e32 v21, v123
	v_mov_b32_e32 v20, v123
	v_mov_b32_e32 v19, v123
	v_mov_b32_e32 v18, v123
	v_mov_b32_e32 v17, v123
	v_mov_b32_e32 v16, v123
	v_mov_b32_e32 v7, v123
	v_mov_b32_e32 v6, v123
	v_mov_b32_e32 v5, v123
	v_mov_b32_e32 v4, v123
	v_mov_b32_e32 v3, v123
	v_mov_b32_e32 v2, v123
	v_mov_b32_e32 v1, v123
	v_mov_b32_e32 v0, v123
	s_cbranch_vccnz .LBB0_643
	s_add_u32 s51, s36, 0x100
	v_mov_b32_e32 v0, 0
	s_addc_u32 s52, s37, 0
	s_mov_b32 s38, 0
	v_mov_b32_e32 v1, v0
	v_mov_b32_e32 v2, v0
	v_mov_b32_e32 v3, v0
	v_mov_b32_e32 v4, v0
	v_mov_b32_e32 v5, v0
	v_mov_b32_e32 v6, v0
	v_mov_b32_e32 v7, v0
	v_mov_b32_e32 v16, v0
	v_mov_b32_e32 v17, v0
	v_mov_b32_e32 v18, v0
	v_mov_b32_e32 v19, v0
	v_mov_b32_e32 v20, v0
	v_mov_b32_e32 v21, v0
	v_mov_b32_e32 v22, v0
	v_mov_b32_e32 v23, v0
	v_mov_b32_e32 v32, v0
	v_mov_b32_e32 v33, v0
	v_mov_b32_e32 v34, v0
	v_mov_b32_e32 v35, v0
	v_mov_b32_e32 v36, v0
	v_mov_b32_e32 v37, v0
	v_mov_b32_e32 v38, v0
	v_mov_b32_e32 v39, v0
	v_mov_b32_e32 v48, v0
	v_mov_b32_e32 v49, v0
	v_mov_b32_e32 v50, v0
	v_mov_b32_e32 v51, v0
	v_mov_b32_e32 v52, v0
	v_mov_b32_e32 v53, v0
	v_mov_b32_e32 v54, v0
	v_mov_b32_e32 v55, v0
	v_mov_b32_e32 v8, v0
	v_mov_b32_e32 v9, v0
	v_mov_b32_e32 v10, v0
	v_mov_b32_e32 v11, v0
	v_mov_b32_e32 v12, v0
	v_mov_b32_e32 v13, v0
	v_mov_b32_e32 v14, v0
	v_mov_b32_e32 v15, v0
	v_mov_b32_e32 v24, v0
	v_mov_b32_e32 v25, v0
	v_mov_b32_e32 v26, v0
	v_mov_b32_e32 v27, v0
	v_mov_b32_e32 v28, v0
	v_mov_b32_e32 v29, v0
	v_mov_b32_e32 v30, v0
	v_mov_b32_e32 v31, v0
	v_mov_b32_e32 v40, v0
	v_mov_b32_e32 v41, v0
	v_mov_b32_e32 v42, v0
	v_mov_b32_e32 v43, v0
	v_mov_b32_e32 v44, v0
	v_mov_b32_e32 v45, v0
	v_mov_b32_e32 v46, v0
	v_mov_b32_e32 v47, v0
	v_mov_b32_e32 v56, v0
	v_mov_b32_e32 v57, v0
	v_mov_b32_e32 v58, v0
	v_mov_b32_e32 v59, v0
	v_mov_b32_e32 v60, v0
	v_mov_b32_e32 v61, v0
	v_mov_b32_e32 v62, v0
	v_mov_b32_e32 v63, v0
	v_mov_b32_e32 v64, v0
	v_mov_b32_e32 v65, v0
	v_mov_b32_e32 v66, v0
	v_mov_b32_e32 v67, v0
	v_mov_b32_e32 v68, v0
	v_mov_b32_e32 v69, v0
	v_mov_b32_e32 v70, v0
	v_mov_b32_e32 v71, v0
	v_mov_b32_e32 v80, v0
	v_mov_b32_e32 v81, v0
	v_mov_b32_e32 v82, v0
	v_mov_b32_e32 v83, v0
	v_mov_b32_e32 v84, v0
	v_mov_b32_e32 v85, v0
	v_mov_b32_e32 v86, v0
	v_mov_b32_e32 v87, v0
	v_mov_b32_e32 v96, v0
	v_mov_b32_e32 v97, v0
	v_mov_b32_e32 v98, v0
	v_mov_b32_e32 v99, v0
	v_mov_b32_e32 v100, v0
	v_mov_b32_e32 v101, v0
	v_mov_b32_e32 v102, v0
	v_mov_b32_e32 v103, v0
	v_mov_b32_e32 v112, v0
	v_mov_b32_e32 v113, v0
	v_mov_b32_e32 v114, v0
	v_mov_b32_e32 v115, v0
	v_mov_b32_e32 v116, v0
	v_mov_b32_e32 v117, v0
	v_mov_b32_e32 v118, v0
	v_mov_b32_e32 v119, v0
	v_mov_b32_e32 v72, v0
	v_mov_b32_e32 v73, v0
	v_mov_b32_e32 v74, v0
	v_mov_b32_e32 v75, v0
	v_mov_b32_e32 v76, v0
	v_mov_b32_e32 v77, v0
	v_mov_b32_e32 v78, v0
	v_mov_b32_e32 v79, v0
	v_mov_b32_e32 v88, v0
	v_mov_b32_e32 v89, v0
	v_mov_b32_e32 v90, v0
	v_mov_b32_e32 v91, v0
	v_mov_b32_e32 v92, v0
	v_mov_b32_e32 v93, v0
	v_mov_b32_e32 v94, v0
	v_mov_b32_e32 v95, v0
	v_mov_b32_e32 v104, v0
	v_mov_b32_e32 v105, v0
	v_mov_b32_e32 v106, v0
	v_mov_b32_e32 v107, v0
	v_mov_b32_e32 v108, v0
	v_mov_b32_e32 v109, v0
	v_mov_b32_e32 v110, v0
	v_mov_b32_e32 v111, v0
	v_mov_b32_e32 v124, v0
	v_mov_b32_e32 v125, v0
	v_mov_b32_e32 v126, v0
	v_mov_b32_e32 v127, v0
	v_mov_b32_e32 v120, v0
	v_mov_b32_e32 v121, v0
	v_mov_b32_e32 v122, v0
	v_mov_b32_e32 v123, v0
	.p2align	6

; #define PG8_STAGE(bufoff, gbase, voff) do { _Pragma("unroll") for (int _i = 0; _i < 2; ++_i) \
;         __builtin_amdgcn_global_load_lds((const unsigned*)((const char*)(gbase) + (voff)[_i]), (LAS unsigned*)(lds + (bufoff) + ldsw + _i * 8192), 16, 0, 0); } while (0)
; #define PG8_WAIT_V(n) asm volatile("s_waitcnt vmcnt(" #n ")" ::: "memory")
; #define PG8_BAR __builtin_amdgcn_s_barrier()
; template <class Epi, bool ALIGN_EPI = PG8_ALIGN>
; __device__ __forceinline__ void gemm_phase(LAS unsigned char* lds, const Gemm g, const StaticOrder& S, const Epi& E) {
;     ...
;     f32x4 acc[2][2][4][2];
; #pragma unroll
;     for (int a = 0; a < 2; ++a)
; #pragma unroll
;         for (int b = 0; b < 2; ++b)
; #pragma unroll
;             for (int m = 0; m < 4; ++m)
; #pragma unroll
;                 for (int n = 0; n < 2; ++n) acc[a][b][m][n] = (f32x4){0.f, 0.f, 0.f, 0.f};
;     bf16x8 At[4][2], B0[2][2], B1[2][2];
;     const char* cA = (const char*)g.A + (size_t)cur.pm * tstepA; const char* cB = (const char*)g.Bt + (size_t)cur.pn * tstepB;
;     PG8_STAGE(PG8_SB(0, 0), cB, voffB); PG8_STAGE(PG8_SB(0, 1), cB + hstepB, voffB); PG8_STAGE(PG8_SA(0, 0), cA, voffA); PG8_STAGE(PG8_SA(0, 1), cA + hstepA, voffA);
;     if (wr == 1) PG8_BAR;
;     PG8_WAIT_V(2); PG8_BAR;
;     PG8_STAGE(PG8_SB(1, 0), cB + kstep, voffB); PG8_STAGE(PG8_SA(1, 0), cA + kstep, voffA); PG8_STAGE(PG8_SB(1, 1), cB + hstepB + kstep, voffB);
;     PG8_WAIT_V(6); PG8_BAR;
;     for (;;) {
;         const bool has_next = S.next(ui + 1, nxt);
;         const char* nA = has_next ? (const char*)g.A + (size_t)nxt.pm * tstepA : cA; const char* nB = has_next ? (const char*)g.Bt + (size_t)nxt.pn * tstepB : cB;
;         for (int t = 0; t < nt; t += 2) {
.LBB0_661:
	v_mov_b32_e32 v123, 0
	s_andn2_b64 vcc, exec, s[12:13]
	v_mov_b32_e32 v122, v123
	v_mov_b32_e32 v121, v123
	v_mov_b32_e32 v120, v123
	v_mov_b32_e32 v127, v123
	v_mov_b32_e32 v126, v123
	v_mov_b32_e32 v125, v123
	v_mov_b32_e32 v124, v123
	v_mov_b32_e32 v111, v123
	v_mov_b32_e32 v110, v123
	v_mov_b32_e32 v109, v123
	v_mov_b32_e32 v108, v123
	v_mov_b32_e32 v107, v123
	v_mov_b32_e32 v106, v123
	v_mov_b32_e32 v105, v123
	v_mov_b32_e32 v104, v123
	v_mov_b32_e32 v95, v123
	v_mov_b32_e32 v94, v123
	v_mov_b32_e32 v93, v123
	v_mov_b32_e32 v92, v123
	v_mov_b32_e32 v91, v123
	v_mov_b32_e32 v90, v123
	v_mov_b32_e32 v89, v123
	v_mov_b32_e32 v88, v123
	v_mov_b32_e32 v79, v123
	v_mov_b32_e32 v78, v123
	v_mov_b32_e32 v77, v123
	v_mov_b32_e32 v76, v123
	v_mov_b32_e32 v75, v123
	v_mov_b32_e32 v74, v123
	v_mov_b32_e32 v73, v123
	v_mov_b32_e32 v72, v123
	v_mov_b32_e32 v119, v123
	v_mov_b32_e32 v118, v123
	v_mov_b32_e32 v117, v123
	v_mov_b32_e32 v116, v123
	v_mov_b32_e32 v115, v123
	v_mov_b32_e32 v114, v123
	v_mov_b32_e32 v113, v123
	v_mov_b32_e32 v112, v123
	v_mov_b32_e32 v103, v123
	v_mov_b32_e32 v102, v123
	v_mov_b32_e32 v101, v123
	v_mov_b32_e32 v100, v123
	v_mov_b32_e32 v99, v123
	v_mov_b32_e32 v98, v123
	v_mov_b32_e32 v97, v123
	v_mov_b32_e32 v96, v123
	v_mov_b32_e32 v87, v123
	v_mov_b32_e32 v86, v123
	v_mov_b32_e32 v85, v123
	v_mov_b32_e32 v84, v123
	v_mov_b32_e32 v83, v123
	v_mov_b32_e32 v82, v123
	v_mov_b32_e32 v81, v123
	v_mov_b32_e32 v80, v123
	v_mov_b32_e32 v71, v123
	v_mov_b32_e32 v70, v123
	v_mov_b32_e32 v69, v123
	v_mov_b32_e32 v68, v123
	v_mov_b32_e32 v67, v123
	v_mov_b32_e32 v66, v123
	v_mov_b32_e32 v65, v123
	v_mov_b32_e32 v64, v123
	v_mov_b32_e32 v63, v123
	v_mov_b32_e32 v62, v123
	v_mov_b32_e32 v61, v123
	v_mov_b32_e32 v60, v123
	v_mov_b32_e32 v59, v123
	v_mov_b32_e32 v58, v123
	v_mov_b32_e32 v57, v123
	v_mov_b32_e32 v56, v123
	v_mov_b32_e32 v47, v123
	v_mov_b32_e32 v46, v123
	v_mov_b32_e32 v45, v123
	v_mov_b32_e32 v44, v123
	v_mov_b32_e32 v43, v123
	v_mov_b32_e32 v42, v123
	v_mov_b32_e32 v41, v123
	v_mov_b32_e32 v40, v123
	v_mov_b32_e32 v31, v123
	v_mov_b32_e32 v30, v123
	v_mov_b32_e32 v29, v123
	v_mov_b32_e32 v28, v123
	v_mov_b32_e32 v27, v123
	v_mov_b32_e32 v26, v123
	v_mov_b32_e32 v25, v123
	v_mov_b32_e32 v24, v123
	v_mov_b32_e32 v15, v123
	v_mov_b32_e32 v14, v123
	v_mov_b32_e32 v13, v123
	v_mov_b32_e32 v12, v123
	v_mov_b32_e32 v11, v123
	v_mov_b32_e32 v10, v123
	v_mov_b32_e32 v9, v123
	v_mov_b32_e32 v8, v123
	v_mov_b32_e32 v55, v123
	v_mov_b32_e32 v54, v123
	v_mov_b32_e32 v53, v123
	v_mov_b32_e32 v52, v123
	v_mov_b32_e32 v51, v123
	v_mov_b32_e32 v50, v123
	v_mov_b32_e32 v49, v123
	v_mov_b32_e32 v48, v123
	v_mov_b32_e32 v39, v123
	v_mov_b32_e32 v38, v123
	v_mov_b32_e32 v37, v123
	v_mov_b32_e32 v36, v123
	v_mov_b32_e32 v35, v123
	v_mov_b32_e32 v34, v123
	v_mov_b32_e32 v33, v123
	v_mov_b32_e32 v32, v123
	v_mov_b32_e32 v23, v123
	v_mov_b32_e32 v22, v123
	v_mov_b32_e32 v21, v123
	v_mov_b32_e32 v20, v123
	v_mov_b32_e32 v19, v123
	v_mov_b32_e32 v18, v123
	v_mov_b32_e32 v17, v123
	v_mov_b32_e32 v16, v123
	v_mov_b32_e32 v7, v123
	v_mov_b32_e32 v6, v123
	v_mov_b32_e32 v5, v123
	v_mov_b32_e32 v4, v123
	v_mov_b32_e32 v3, v123
	v_mov_b32_e32 v2, v123
	v_mov_b32_e32 v1, v123
	v_mov_b32_e32 v0, v123
	s_cbranch_vccnz .LBB0_664
	s_add_u32 s34, s36, 0x100
	v_mov_b32_e32 v0, 0
	s_addc_u32 s52, s37, 0
	s_mov_b32 s38, 0
	v_mov_b32_e32 v1, v0
	v_mov_b32_e32 v2, v0
	v_mov_b32_e32 v3, v0
	v_mov_b32_e32 v4, v0
	v_mov_b32_e32 v5, v0
	v_mov_b32_e32 v6, v0
	v_mov_b32_e32 v7, v0
	v_mov_b32_e32 v16, v0
	v_mov_b32_e32 v17, v0
	v_mov_b32_e32 v18, v0
	v_mov_b32_e32 v19, v0
	v_mov_b32_e32 v20, v0
	v_mov_b32_e32 v21, v0
	v_mov_b32_e32 v22, v0
	v_mov_b32_e32 v23, v0
	v_mov_b32_e32 v32, v0
	v_mov_b32_e32 v33, v0
	v_mov_b32_e32 v34, v0
	v_mov_b32_e32 v35, v0
	v_mov_b32_e32 v36, v0
	v_mov_b32_e32 v37, v0
	v_mov_b32_e32 v38, v0
	v_mov_b32_e32 v39, v0
	v_mov_b32_e32 v48, v0
	v_mov_b32_e32 v49, v0
	v_mov_b32_e32 v50, v0
	v_mov_b32_e32 v51, v0
	v_mov_b32_e32 v52, v0
	v_mov_b32_e32 v53, v0
	v_mov_b32_e32 v54, v0
	v_mov_b32_e32 v55, v0
	v_mov_b32_e32 v8, v0
	v_mov_b32_e32 v9, v0
	v_mov_b32_e32 v10, v0
	v_mov_b32_e32 v11, v0
	v_mov_b32_e32 v12, v0
	v_mov_b32_e32 v13, v0
	v_mov_b32_e32 v14, v0
	v_mov_b32_e32 v15, v0
	v_mov_b32_e32 v24, v0
	v_mov_b32_e32 v25, v0
	v_mov_b32_e32 v26, v0
	v_mov_b32_e32 v27, v0
	v_mov_b32_e32 v28, v0
	v_mov_b32_e32 v29, v0
	v_mov_b32_e32 v30, v0
	v_mov_b32_e32 v31, v0
	v_mov_b32_e32 v40, v0
	v_mov_b32_e32 v41, v0
	v_mov_b32_e32 v42, v0
	v_mov_b32_e32 v43, v0
	v_mov_b32_e32 v44, v0
	v_mov_b32_e32 v45, v0
	v_mov_b32_e32 v46, v0
	v_mov_b32_e32 v47, v0
	v_mov_b32_e32 v56, v0
	v_mov_b32_e32 v57, v0
	v_mov_b32_e32 v58, v0
	v_mov_b32_e32 v59, v0
	v_mov_b32_e32 v60, v0
	v_mov_b32_e32 v61, v0
	v_mov_b32_e32 v62, v0
	v_mov_b32_e32 v63, v0
	v_mov_b32_e32 v64, v0
	v_mov_b32_e32 v65, v0
	v_mov_b32_e32 v66, v0
	v_mov_b32_e32 v67, v0
	v_mov_b32_e32 v68, v0
	v_mov_b32_e32 v69, v0
	v_mov_b32_e32 v70, v0
	v_mov_b32_e32 v71, v0
	v_mov_b32_e32 v80, v0
	v_mov_b32_e32 v81, v0
	v_mov_b32_e32 v82, v0
	v_mov_b32_e32 v83, v0
	v_mov_b32_e32 v84, v0
	v_mov_b32_e32 v85, v0
	v_mov_b32_e32 v86, v0
	v_mov_b32_e32 v87, v0
	v_mov_b32_e32 v96, v0
	v_mov_b32_e32 v97, v0
	v_mov_b32_e32 v98, v0
	v_mov_b32_e32 v99, v0
	v_mov_b32_e32 v100, v0
	v_mov_b32_e32 v101, v0
	v_mov_b32_e32 v102, v0
	v_mov_b32_e32 v103, v0
	v_mov_b32_e32 v112, v0
	v_mov_b32_e32 v113, v0
	v_mov_b32_e32 v114, v0
	v_mov_b32_e32 v115, v0
	v_mov_b32_e32 v116, v0
	v_mov_b32_e32 v117, v0
	v_mov_b32_e32 v118, v0
	v_mov_b32_e32 v119, v0
	v_mov_b32_e32 v72, v0
	v_mov_b32_e32 v73, v0
	v_mov_b32_e32 v74, v0
	v_mov_b32_e32 v75, v0
	v_mov_b32_e32 v76, v0
	v_mov_b32_e32 v77, v0
	v_mov_b32_e32 v78, v0
	v_mov_b32_e32 v79, v0
	v_mov_b32_e32 v88, v0
	v_mov_b32_e32 v89, v0
	v_mov_b32_e32 v90, v0
	v_mov_b32_e32 v91, v0
	v_mov_b32_e32 v92, v0
	v_mov_b32_e32 v93, v0
	v_mov_b32_e32 v94, v0
	v_mov_b32_e32 v95, v0
	v_mov_b32_e32 v104, v0
	v_mov_b32_e32 v105, v0
	v_mov_b32_e32 v106, v0
	v_mov_b32_e32 v107, v0
	v_mov_b32_e32 v108, v0
	v_mov_b32_e32 v109, v0
	v_mov_b32_e32 v110, v0
	v_mov_b32_e32 v111, v0
	v_mov_b32_e32 v124, v0
	v_mov_b32_e32 v125, v0
	v_mov_b32_e32 v126, v0
	v_mov_b32_e32 v127, v0
	v_mov_b32_e32 v120, v0
	v_mov_b32_e32 v121, v0
	v_mov_b32_e32 v122, v0
	v_mov_b32_e32 v123, v0
	.p2align	6

; #define PG8_STAGE(bufoff, gbase, voff) do { _Pragma("unroll") for (int _i = 0; _i < 2; ++_i) \
;         __builtin_amdgcn_global_load_lds((const unsigned*)((const char*)(gbase) + (voff)[_i]), (LAS unsigned*)(lds + (bufoff) + ldsw + _i * 8192), 16, 0, 0); } while (0)
; #define PG8_WAIT_V(n) asm volatile("s_waitcnt vmcnt(" #n ")" ::: "memory")
; #define PG8_BAR __builtin_amdgcn_s_barrier()
; template <class Epi, bool ALIGN_EPI = PG8_ALIGN>
; __device__ __forceinline__ void gemm_phase(LAS unsigned char* lds, const Gemm g, const StaticOrder& S, const Epi& E) {
;     ...
;     const char* cA = (const char*)g.A + (size_t)cur.pm * tstepA; const char* cB = (const char*)g.Bt + (size_t)cur.pn * tstepB;
;     PG8_STAGE(PG8_SB(0, 0), cB, voffB); PG8_STAGE(PG8_SB(0, 1), cB + hstepB, voffB); PG8_STAGE(PG8_SA(0, 0), cA, voffA); PG8_STAGE(PG8_SA(0, 1), cA + hstepA, voffA);
;     if (wr == 1) PG8_BAR;
;     PG8_WAIT_V(2); PG8_BAR;
;     PG8_STAGE(PG8_SB(1, 0), cB + kstep, voffB); PG8_STAGE(PG8_SA(1, 0), cA + kstep, voffA); PG8_STAGE(PG8_SB(1, 1), cB + hstepB + kstep, voffB);
;     PG8_WAIT_V(6); PG8_BAR;
;     for (;;) {
;         const bool has_next = S.next(ui + 1, nxt);
;         const char* nA = has_next ? (const char*)g.A + (size_t)nxt.pm * tstepA : cA; const char* nB = has_next ? (const char*)g.Bt + (size_t)nxt.pn * tstepB : cB;
;         for (int t = 0; t < nt; t += 2) {
;             const bool last = (t == nt - 2);
;             const char* a1 = cA + (size_t)(t + 1) * kstep;
;             const char* a2 = last ? nA : cA + (size_t)(t + 2) * kstep; const char* b2 = last ? nB : cB + (size_t)(t + 2) * kstep;
.LBB0_899:
	s_ashr_i32 s25, s24, 31
	s_lshl_b64 s[20:21], s[24:25], 20
	s_add_u32 s38, s64, s20
	v_mov_b32_e32 v123, 0
	s_addc_u32 s39, s65, s21
	s_andn2_b64 vcc, exec, s[14:15]
	v_mov_b32_e32 v122, v123
	v_mov_b32_e32 v121, v123
	v_mov_b32_e32 v120, v123
	v_mov_b32_e32 v127, v123
	v_mov_b32_e32 v126, v123
	v_mov_b32_e32 v125, v123
	v_mov_b32_e32 v124, v123
	v_mov_b32_e32 v111, v123
	v_mov_b32_e32 v110, v123
	v_mov_b32_e32 v109, v123
	v_mov_b32_e32 v108, v123
	v_mov_b32_e32 v107, v123
	v_mov_b32_e32 v106, v123
	v_mov_b32_e32 v105, v123
	v_mov_b32_e32 v104, v123
	v_mov_b32_e32 v95, v123
	v_mov_b32_e32 v94, v123
	v_mov_b32_e32 v93, v123
	v_mov_b32_e32 v92, v123
	v_mov_b32_e32 v91, v123
	v_mov_b32_e32 v90, v123
	v_mov_b32_e32 v89, v123
	v_mov_b32_e32 v88, v123
	v_mov_b32_e32 v79, v123
	v_mov_b32_e32 v78, v123
	v_mov_b32_e32 v77, v123
	v_mov_b32_e32 v76, v123
	v_mov_b32_e32 v75, v123
	v_mov_b32_e32 v74, v123
	v_mov_b32_e32 v73, v123
	v_mov_b32_e32 v72, v123
	v_mov_b32_e32 v119, v123
	v_mov_b32_e32 v118, v123
	v_mov_b32_e32 v117, v123
	v_mov_b32_e32 v116, v123
	v_mov_b32_e32 v115, v123
	v_mov_b32_e32 v114, v123
	v_mov_b32_e32 v113, v123
	v_mov_b32_e32 v112, v123
	v_mov_b32_e32 v103, v123
	v_mov_b32_e32 v102, v123
	v_mov_b32_e32 v101, v123
	v_mov_b32_e32 v100, v123
	v_mov_b32_e32 v99, v123
	v_mov_b32_e32 v98, v123
	v_mov_b32_e32 v97, v123
	v_mov_b32_e32 v96, v123
	v_mov_b32_e32 v87, v123
	v_mov_b32_e32 v86, v123
	v_mov_b32_e32 v85, v123
	v_mov_b32_e32 v84, v123
	v_mov_b32_e32 v83, v123
	v_mov_b32_e32 v82, v123
	v_mov_b32_e32 v81, v123
	v_mov_b32_e32 v80, v123
	v_mov_b32_e32 v71, v123
	v_mov_b32_e32 v70, v123
	v_mov_b32_e32 v69, v123
	v_mov_b32_e32 v68, v123
	v_mov_b32_e32 v67, v123
	v_mov_b32_e32 v66, v123
	v_mov_b32_e32 v65, v123
	v_mov_b32_e32 v64, v123
	v_mov_b32_e32 v63, v123
	v_mov_b32_e32 v62, v123
	v_mov_b32_e32 v61, v123
	v_mov_b32_e32 v60, v123
	v_mov_b32_e32 v59, v123
	v_mov_b32_e32 v58, v123
	v_mov_b32_e32 v57, v123
	v_mov_b32_e32 v56, v123
	v_mov_b32_e32 v47, v123
	v_mov_b32_e32 v46, v123
	v_mov_b32_e32 v45, v123
	v_mov_b32_e32 v44, v123
	v_mov_b32_e32 v43, v123
	v_mov_b32_e32 v42, v123
	v_mov_b32_e32 v41, v123
	v_mov_b32_e32 v40, v123
	v_mov_b32_e32 v31, v123
	v_mov_b32_e32 v30, v123
	v_mov_b32_e32 v29, v123
	v_mov_b32_e32 v28, v123
	v_mov_b32_e32 v27, v123
	v_mov_b32_e32 v26, v123
	v_mov_b32_e32 v25, v123
	v_mov_b32_e32 v24, v123
	v_mov_b32_e32 v15, v123
	v_mov_b32_e32 v14, v123
	v_mov_b32_e32 v13, v123
	v_mov_b32_e32 v12, v123
	v_mov_b32_e32 v11, v123
	v_mov_b32_e32 v10, v123
	v_mov_b32_e32 v9, v123
	v_mov_b32_e32 v8, v123
	v_mov_b32_e32 v55, v123
	v_mov_b32_e32 v54, v123
	v_mov_b32_e32 v53, v123
	v_mov_b32_e32 v52, v123
	v_mov_b32_e32 v51, v123
	v_mov_b32_e32 v50, v123
	v_mov_b32_e32 v49, v123
	v_mov_b32_e32 v48, v123
	v_mov_b32_e32 v39, v123
	v_mov_b32_e32 v38, v123
	v_mov_b32_e32 v37, v123
	v_mov_b32_e32 v36, v123
	v_mov_b32_e32 v35, v123
	v_mov_b32_e32 v34, v123
	v_mov_b32_e32 v33, v123
	v_mov_b32_e32 v32, v123
	v_mov_b32_e32 v23, v123
	v_mov_b32_e32 v22, v123
	v_mov_b32_e32 v21, v123
	v_mov_b32_e32 v20, v123
	v_mov_b32_e32 v19, v123
	v_mov_b32_e32 v18, v123
	v_mov_b32_e32 v17, v123
	v_mov_b32_e32 v16, v123
	v_mov_b32_e32 v7, v123
	v_mov_b32_e32 v6, v123
	v_mov_b32_e32 v5, v123
	v_mov_b32_e32 v4, v123
	v_mov_b32_e32 v3, v123
	v_mov_b32_e32 v2, v123
	v_mov_b32_e32 v1, v123
	v_mov_b32_e32 v0, v123
	s_cbranch_vccnz .LBB0_902
	s_and_b64 s[4:5], s[4:5], exec
	s_cselect_b32 s25, s39, s43
	s_cselect_b32 s52, s38, s42
	s_add_u32 s4, s42, 0x80080
	s_addc_u32 s5, s43, 0
	s_add_u32 s42, s40, 0x100
	v_mov_b32_e32 v0, 0
	s_addc_u32 s43, s41, 0
	s_mov_b32 s40, 0
	v_mov_b32_e32 v1, v0
	v_mov_b32_e32 v2, v0
	v_mov_b32_e32 v3, v0
	v_mov_b32_e32 v4, v0
	v_mov_b32_e32 v5, v0
	v_mov_b32_e32 v6, v0
	v_mov_b32_e32 v7, v0
	v_mov_b32_e32 v16, v0
	v_mov_b32_e32 v17, v0
	v_mov_b32_e32 v18, v0
	v_mov_b32_e32 v19, v0
	v_mov_b32_e32 v20, v0
	v_mov_b32_e32 v21, v0
	v_mov_b32_e32 v22, v0
	v_mov_b32_e32 v23, v0
	v_mov_b32_e32 v32, v0
	v_mov_b32_e32 v33, v0
	v_mov_b32_e32 v34, v0
	v_mov_b32_e32 v35, v0
	v_mov_b32_e32 v36, v0
	v_mov_b32_e32 v37, v0
	v_mov_b32_e32 v38, v0
	v_mov_b32_e32 v39, v0
	v_mov_b32_e32 v48, v0
	v_mov_b32_e32 v49, v0
	v_mov_b32_e32 v50, v0
	v_mov_b32_e32 v51, v0
	v_mov_b32_e32 v52, v0
	v_mov_b32_e32 v53, v0
	v_mov_b32_e32 v54, v0
	v_mov_b32_e32 v55, v0
	v_mov_b32_e32 v8, v0
	v_mov_b32_e32 v9, v0
	v_mov_b32_e32 v10, v0
	v_mov_b32_e32 v11, v0
	v_mov_b32_e32 v12, v0
	v_mov_b32_e32 v13, v0
	v_mov_b32_e32 v14, v0
	v_mov_b32_e32 v15, v0
	v_mov_b32_e32 v24, v0
	v_mov_b32_e32 v25, v0
	v_mov_b32_e32 v26, v0
	v_mov_b32_e32 v27, v0
	v_mov_b32_e32 v28, v0
	v_mov_b32_e32 v29, v0
	v_mov_b32_e32 v30, v0
	v_mov_b32_e32 v31, v0
	v_mov_b32_e32 v40, v0
	v_mov_b32_e32 v41, v0
	v_mov_b32_e32 v42, v0
	v_mov_b32_e32 v43, v0
	v_mov_b32_e32 v44, v0
	v_mov_b32_e32 v45, v0
	v_mov_b32_e32 v46, v0
	v_mov_b32_e32 v47, v0
	v_mov_b32_e32 v56, v0
	v_mov_b32_e32 v57, v0
	v_mov_b32_e32 v58, v0
	v_mov_b32_e32 v59, v0
	v_mov_b32_e32 v60, v0
	v_mov_b32_e32 v61, v0
	v_mov_b32_e32 v62, v0
	v_mov_b32_e32 v63, v0
	v_mov_b32_e32 v64, v0
	v_mov_b32_e32 v65, v0
	v_mov_b32_e32 v66, v0
	v_mov_b32_e32 v67, v0
	v_mov_b32_e32 v68, v0
	v_mov_b32_e32 v69, v0
	v_mov_b32_e32 v70, v0
	v_mov_b32_e32 v71, v0
	v_mov_b32_e32 v80, v0
	v_mov_b32_e32 v81, v0
	v_mov_b32_e32 v82, v0
	v_mov_b32_e32 v83, v0
	v_mov_b32_e32 v84, v0
	v_mov_b32_e32 v85, v0
	v_mov_b32_e32 v86, v0
	v_mov_b32_e32 v87, v0
	v_mov_b32_e32 v96, v0
	v_mov_b32_e32 v97, v0
	v_mov_b32_e32 v98, v0
	v_mov_b32_e32 v99, v0
	v_mov_b32_e32 v100, v0
	v_mov_b32_e32 v101, v0
	v_mov_b32_e32 v102, v0
	v_mov_b32_e32 v103, v0
	v_mov_b32_e32 v112, v0
	v_mov_b32_e32 v113, v0
	v_mov_b32_e32 v114, v0
	v_mov_b32_e32 v115, v0
	v_mov_b32_e32 v116, v0
	v_mov_b32_e32 v117, v0
	v_mov_b32_e32 v118, v0
	v_mov_b32_e32 v119, v0
	v_mov_b32_e32 v72, v0
	v_mov_b32_e32 v73, v0
	v_mov_b32_e32 v74, v0
	v_mov_b32_e32 v75, v0
	v_mov_b32_e32 v76, v0
	v_mov_b32_e32 v77, v0
	v_mov_b32_e32 v78, v0
	v_mov_b32_e32 v79, v0
	v_mov_b32_e32 v88, v0
	v_mov_b32_e32 v89, v0
	v_mov_b32_e32 v90, v0
	v_mov_b32_e32 v91, v0
	v_mov_b32_e32 v92, v0
	v_mov_b32_e32 v93, v0
	v_mov_b32_e32 v94, v0
	v_mov_b32_e32 v95, v0
	v_mov_b32_e32 v104, v0
	v_mov_b32_e32 v105, v0
	v_mov_b32_e32 v106, v0
	v_mov_b32_e32 v107, v0
	v_mov_b32_e32 v108, v0
	v_mov_b32_e32 v109, v0
	v_mov_b32_e32 v110, v0
	v_mov_b32_e32 v111, v0
	v_mov_b32_e32 v124, v0
	v_mov_b32_e32 v125, v0
	v_mov_b32_e32 v126, v0
	v_mov_b32_e32 v127, v0
	v_mov_b32_e32 v120, v0
	v_mov_b32_e32 v121, v0
	v_mov_b32_e32 v122, v0
	v_mov_b32_e32 v123, v0
	.p2align	6

; #define PG8_STAGE(bufoff, gbase, voff) do { _Pragma("unroll") for (int _i = 0; _i < 2; ++_i) \
;         __builtin_amdgcn_global_load_lds((const unsigned*)((const char*)(gbase) + (voff)[_i]), (LAS unsigned*)(lds + (bufoff) + ldsw + _i * 8192), 16, 0, 0); } while (0)
; #define PG8_WAIT_V(n) asm volatile("s_waitcnt vmcnt(" #n ")" ::: "memory")
; #define PG8_BAR __builtin_amdgcn_s_barrier()
; template <class Epi, bool ALIGN_EPI = PG8_ALIGN>
; __device__ __forceinline__ void gemm_phase(LAS unsigned char* lds, const Gemm g, const StaticOrder& S, const Epi& E) {
;     ...
;     const char* cA = (const char*)g.A + (size_t)cur.pm * tstepA; const char* cB = (const char*)g.Bt + (size_t)cur.pn * tstepB;
;     PG8_STAGE(PG8_SB(0, 0), cB, voffB); PG8_STAGE(PG8_SB(0, 1), cB + hstepB, voffB); PG8_STAGE(PG8_SA(0, 0), cA, voffA); PG8_STAGE(PG8_SA(0, 1), cA + hstepA, voffA);
;     if (wr == 1) PG8_BAR;
;     PG8_WAIT_V(2); PG8_BAR;
;     PG8_STAGE(PG8_SB(1, 0), cB + kstep, voffB); PG8_STAGE(PG8_SA(1, 0), cA + kstep, voffA); PG8_STAGE(PG8_SB(1, 1), cB + hstepB + kstep, voffB);
;     PG8_WAIT_V(6); PG8_BAR;
;     for (;;) {
;         const bool has_next = S.next(ui + 1, nxt);
;         const char* nA = has_next ? (const char*)g.A + (size_t)nxt.pm * tstepA : cA; const char* nB = has_next ? (const char*)g.Bt + (size_t)nxt.pn * tstepB : cB;
;         for (int t = 0; t < nt; t += 2) {
;             const bool last = (t == nt - 2);
;             const char* a1 = cA + (size_t)(t + 1) * kstep;
;             const char* a2 = last ? nA : cA + (size_t)(t + 2) * kstep; const char* b2 = last ? nB : cB + (size_t)(t + 2) * kstep;
.LBB0_1026:
	s_ashr_i32 s17, s16, 31
	s_lshl_b64 s[20:21], s[16:17], 20
	s_add_u32 s42, s58, s20
	v_mov_b32_e32 v127, 0
	s_addc_u32 s43, s59, s21
	s_andn2_b64 vcc, exec, s[12:13]
	v_mov_b32_e32 v126, v127
	v_mov_b32_e32 v125, v127
	v_mov_b32_e32 v124, v127
	v_mov_b32_e32 v119, v127
	v_mov_b32_e32 v118, v127
	v_mov_b32_e32 v117, v127
	v_mov_b32_e32 v116, v127
	v_mov_b32_e32 v111, v127
	v_mov_b32_e32 v110, v127
	v_mov_b32_e32 v109, v127
	v_mov_b32_e32 v108, v127
	v_mov_b32_e32 v103, v127
	v_mov_b32_e32 v102, v127
	v_mov_b32_e32 v101, v127
	v_mov_b32_e32 v100, v127
	v_mov_b32_e32 v95, v127
	v_mov_b32_e32 v94, v127
	v_mov_b32_e32 v93, v127
	v_mov_b32_e32 v92, v127
	v_mov_b32_e32 v87, v127
	v_mov_b32_e32 v86, v127
	v_mov_b32_e32 v85, v127
	v_mov_b32_e32 v84, v127
	v_mov_b32_e32 v79, v127
	v_mov_b32_e32 v78, v127
	v_mov_b32_e32 v77, v127
	v_mov_b32_e32 v76, v127
	v_mov_b32_e32 v71, v127
	v_mov_b32_e32 v70, v127
	v_mov_b32_e32 v69, v127
	v_mov_b32_e32 v68, v127
	v_mov_b32_e32 v123, v127
	v_mov_b32_e32 v122, v127
	v_mov_b32_e32 v121, v127
	v_mov_b32_e32 v120, v127
	v_mov_b32_e32 v115, v127
	v_mov_b32_e32 v114, v127
	v_mov_b32_e32 v113, v127
	v_mov_b32_e32 v112, v127
	v_mov_b32_e32 v107, v127
	v_mov_b32_e32 v106, v127
	v_mov_b32_e32 v105, v127
	v_mov_b32_e32 v104, v127
	v_mov_b32_e32 v99, v127
	v_mov_b32_e32 v98, v127
	v_mov_b32_e32 v97, v127
	v_mov_b32_e32 v96, v127
	v_mov_b32_e32 v91, v127
	v_mov_b32_e32 v90, v127
	v_mov_b32_e32 v89, v127
	v_mov_b32_e32 v88, v127
	v_mov_b32_e32 v83, v127
	v_mov_b32_e32 v82, v127
	v_mov_b32_e32 v81, v127
	v_mov_b32_e32 v80, v127
	v_mov_b32_e32 v75, v127
	v_mov_b32_e32 v74, v127
	v_mov_b32_e32 v73, v127
	v_mov_b32_e32 v72, v127
	v_mov_b32_e32 v67, v127
	v_mov_b32_e32 v66, v127
	v_mov_b32_e32 v65, v127
	v_mov_b32_e32 v64, v127
	v_mov_b32_e32 v63, v127
	v_mov_b32_e32 v62, v127
	v_mov_b32_e32 v61, v127
	v_mov_b32_e32 v60, v127
	v_mov_b32_e32 v55, v127
	v_mov_b32_e32 v54, v127
	v_mov_b32_e32 v53, v127
	v_mov_b32_e32 v52, v127
	v_mov_b32_e32 v47, v127
	v_mov_b32_e32 v46, v127
	v_mov_b32_e32 v45, v127
	v_mov_b32_e32 v44, v127
	v_mov_b32_e32 v39, v127
	v_mov_b32_e32 v38, v127
	v_mov_b32_e32 v37, v127
	v_mov_b32_e32 v36, v127
	v_mov_b32_e32 v31, v127
	v_mov_b32_e32 v30, v127
	v_mov_b32_e32 v29, v127
	v_mov_b32_e32 v28, v127
	v_mov_b32_e32 v23, v127
	v_mov_b32_e32 v22, v127
	v_mov_b32_e32 v21, v127
	v_mov_b32_e32 v20, v127
	v_mov_b32_e32 v15, v127
	v_mov_b32_e32 v14, v127
	v_mov_b32_e32 v13, v127
	v_mov_b32_e32 v12, v127
	v_mov_b32_e32 v7, v127
	v_mov_b32_e32 v6, v127
	v_mov_b32_e32 v5, v127
	v_mov_b32_e32 v4, v127
	v_mov_b32_e32 v59, v127
	v_mov_b32_e32 v58, v127
	v_mov_b32_e32 v57, v127
	v_mov_b32_e32 v56, v127
	v_mov_b32_e32 v51, v127
	v_mov_b32_e32 v50, v127
	v_mov_b32_e32 v49, v127
	v_mov_b32_e32 v48, v127
	v_mov_b32_e32 v43, v127
	v_mov_b32_e32 v42, v127
	v_mov_b32_e32 v41, v127
	v_mov_b32_e32 v40, v127
	v_mov_b32_e32 v35, v127
	v_mov_b32_e32 v34, v127
	v_mov_b32_e32 v33, v127
	v_mov_b32_e32 v32, v127
	v_mov_b32_e32 v27, v127
	v_mov_b32_e32 v26, v127
	v_mov_b32_e32 v25, v127
	v_mov_b32_e32 v24, v127
	v_mov_b32_e32 v19, v127
	v_mov_b32_e32 v18, v127
	v_mov_b32_e32 v17, v127
	v_mov_b32_e32 v16, v127
	v_mov_b32_e32 v11, v127
	v_mov_b32_e32 v10, v127
	v_mov_b32_e32 v9, v127
	v_mov_b32_e32 v8, v127
	v_mov_b32_e32 v3, v127
	v_mov_b32_e32 v2, v127
	v_mov_b32_e32 v1, v127
	v_mov_b32_e32 v0, v127
	s_cbranch_vccnz .LBB0_1029
	s_and_b64 s[2:3], s[2:3], exec
	s_cselect_b32 s17, s43, s37
	s_cselect_b32 s27, s42, s36
	s_add_u32 s2, s36, 0x80080
	s_addc_u32 s3, s37, 0
	s_add_u32 s29, s24, 0x100
	v_mov_b32_e32 v0, 0
	s_addc_u32 s30, s25, 0
	s_mov_b32 s24, 0
	v_mov_b32_e32 v1, v0
	v_mov_b32_e32 v2, v0
	v_mov_b32_e32 v3, v0
	v_mov_b32_e32 v8, v0
	v_mov_b32_e32 v9, v0
	v_mov_b32_e32 v10, v0
	v_mov_b32_e32 v11, v0
	v_mov_b32_e32 v16, v0
	v_mov_b32_e32 v17, v0
	v_mov_b32_e32 v18, v0
	v_mov_b32_e32 v19, v0
	v_mov_b32_e32 v24, v0
	v_mov_b32_e32 v25, v0
	v_mov_b32_e32 v26, v0
	v_mov_b32_e32 v27, v0
	v_mov_b32_e32 v32, v0
	v_mov_b32_e32 v33, v0
	v_mov_b32_e32 v34, v0
	v_mov_b32_e32 v35, v0
	v_mov_b32_e32 v40, v0
	v_mov_b32_e32 v41, v0
	v_mov_b32_e32 v42, v0
	v_mov_b32_e32 v43, v0
	v_mov_b32_e32 v48, v0
	v_mov_b32_e32 v49, v0
	v_mov_b32_e32 v50, v0
	v_mov_b32_e32 v51, v0
	v_mov_b32_e32 v56, v0
	v_mov_b32_e32 v57, v0
	v_mov_b32_e32 v58, v0
	v_mov_b32_e32 v59, v0
	v_mov_b32_e32 v4, v0
	v_mov_b32_e32 v5, v0
	v_mov_b32_e32 v6, v0
	v_mov_b32_e32 v7, v0
	v_mov_b32_e32 v12, v0
	v_mov_b32_e32 v13, v0
	v_mov_b32_e32 v14, v0
	v_mov_b32_e32 v15, v0
	v_mov_b32_e32 v20, v0
	v_mov_b32_e32 v21, v0
	v_mov_b32_e32 v22, v0
	v_mov_b32_e32 v23, v0
	v_mov_b32_e32 v28, v0
	v_mov_b32_e32 v29, v0
	v_mov_b32_e32 v30, v0
	v_mov_b32_e32 v31, v0
	v_mov_b32_e32 v36, v0
	v_mov_b32_e32 v37, v0
	v_mov_b32_e32 v38, v0
	v_mov_b32_e32 v39, v0
	v_mov_b32_e32 v44, v0
	v_mov_b32_e32 v45, v0
	v_mov_b32_e32 v46, v0
	v_mov_b32_e32 v47, v0
	v_mov_b32_e32 v52, v0
	v_mov_b32_e32 v53, v0
	v_mov_b32_e32 v54, v0
	v_mov_b32_e32 v55, v0
	v_mov_b32_e32 v60, v0
	v_mov_b32_e32 v61, v0
	v_mov_b32_e32 v62, v0
	v_mov_b32_e32 v63, v0
	v_mov_b32_e32 v64, v0
	v_mov_b32_e32 v65, v0
	v_mov_b32_e32 v66, v0
	v_mov_b32_e32 v67, v0
	v_mov_b32_e32 v72, v0
	v_mov_b32_e32 v73, v0
	v_mov_b32_e32 v74, v0
	v_mov_b32_e32 v75, v0
	v_mov_b32_e32 v80, v0
	v_mov_b32_e32 v81, v0
	v_mov_b32_e32 v82, v0
	v_mov_b32_e32 v83, v0
	v_mov_b32_e32 v88, v0
	v_mov_b32_e32 v89, v0
	v_mov_b32_e32 v90, v0
	v_mov_b32_e32 v91, v0
	v_mov_b32_e32 v96, v0
	v_mov_b32_e32 v97, v0
	v_mov_b32_e32 v98, v0
	v_mov_b32_e32 v99, v0
	v_mov_b32_e32 v104, v0
	v_mov_b32_e32 v105, v0
	v_mov_b32_e32 v106, v0
	v_mov_b32_e32 v107, v0
	v_mov_b32_e32 v112, v0
	v_mov_b32_e32 v113, v0
	v_mov_b32_e32 v114, v0
	v_mov_b32_e32 v115, v0
	v_mov_b32_e32 v120, v0
	v_mov_b32_e32 v121, v0
	v_mov_b32_e32 v122, v0
	v_mov_b32_e32 v123, v0
	v_mov_b32_e32 v68, v0
	v_mov_b32_e32 v69, v0
	v_mov_b32_e32 v70, v0
	v_mov_b32_e32 v71, v0
	v_mov_b32_e32 v76, v0
	v_mov_b32_e32 v77, v0
	v_mov_b32_e32 v78, v0
	v_mov_b32_e32 v79, v0
	v_mov_b32_e32 v84, v0
	v_mov_b32_e32 v85, v0
	v_mov_b32_e32 v86, v0
	v_mov_b32_e32 v87, v0
	v_mov_b32_e32 v92, v0
	v_mov_b32_e32 v93, v0
	v_mov_b32_e32 v94, v0
	v_mov_b32_e32 v95, v0
	v_mov_b32_e32 v100, v0
	v_mov_b32_e32 v101, v0
	v_mov_b32_e32 v102, v0
	v_mov_b32_e32 v103, v0
	v_mov_b32_e32 v108, v0
	v_mov_b32_e32 v109, v0
	v_mov_b32_e32 v110, v0
	v_mov_b32_e32 v111, v0
	v_mov_b32_e32 v116, v0
	v_mov_b32_e32 v117, v0
	v_mov_b32_e32 v118, v0
	v_mov_b32_e32 v119, v0
	v_mov_b32_e32 v124, v0
	v_mov_b32_e32 v125, v0
	v_mov_b32_e32 v126, v0
	v_mov_b32_e32 v127, v0
	.p2align	6

; #define PG8_STAGE(bufoff, gbase, voff) do { _Pragma("unroll") for (int _i = 0; _i < 2; ++_i) \
;         __builtin_amdgcn_global_load_lds((const unsigned*)((const char*)(gbase) + (voff)[_i]), (LAS unsigned*)(lds + (bufoff) + ldsw + _i * 8192), 16, 0, 0); } while (0)
; #define PG8_WAIT_V(n) asm volatile("s_waitcnt vmcnt(" #n ")" ::: "memory")
; #define PG8_BAR __builtin_amdgcn_s_barrier()
; template <class Epi, bool ALIGN_EPI = PG8_ALIGN>
; __device__ __forceinline__ void gemm_phase(LAS unsigned char* lds, const Gemm g, const StaticOrder& S, const Epi& E) {
;     ...
;     f32x4 acc[2][2][4][2];
; #pragma unroll
;     for (int a = 0; a < 2; ++a)
; #pragma unroll
;         for (int b = 0; b < 2; ++b)
; #pragma unroll
;             for (int m = 0; m < 4; ++m)
; #pragma unroll
;                 for (int n = 0; n < 2; ++n) acc[a][b][m][n] = (f32x4){0.f, 0.f, 0.f, 0.f};
;     bf16x8 At[4][2], B0[2][2], B1[2][2];
;     const char* cA = (const char*)g.A + (size_t)cur.pm * tstepA; const char* cB = (const char*)g.Bt + (size_t)cur.pn * tstepB;
;     PG8_STAGE(PG8_SB(0, 0), cB, voffB); PG8_STAGE(PG8_SB(0, 1), cB + hstepB, voffB); PG8_STAGE(PG8_SA(0, 0), cA, voffA); PG8_STAGE(PG8_SA(0, 1), cA + hstepA, voffA);
;     if (wr == 1) PG8_BAR;
;     PG8_WAIT_V(2); PG8_BAR;
;     PG8_STAGE(PG8_SB(1, 0), cB + kstep, voffB); PG8_STAGE(PG8_SA(1, 0), cA + kstep, voffA); PG8_STAGE(PG8_SB(1, 1), cB + hstepB + kstep, voffB);
;     PG8_WAIT_V(6); PG8_BAR;
;     for (;;) {
;         const bool has_next = S.next(ui + 1, nxt);
;         const char* nA = has_next ? (const char*)g.A + (size_t)nxt.pm * tstepA : cA; const char* nB = has_next ? (const char*)g.Bt + (size_t)nxt.pn * tstepB : cB;
;         for (int t = 0; t < nt; t += 2) {
.LBB0_1106:
	v_mov_b32_e32 v127, 0
	s_andn2_b64 vcc, exec, s[12:13]
	v_mov_b32_e32 v126, 0
	v_mov_b32_e32 v125, 0
	v_mov_b32_e32 v124, 0
	v_mov_b32_e32 v123, 0
	v_mov_b32_e32 v122, 0
	v_mov_b32_e32 v121, 0
	v_mov_b32_e32 v120, 0
	v_mov_b32_e32 v101, 0
	v_mov_b32_e32 v100, 0
	v_mov_b32_e32 v103, 0
	v_mov_b32_e32 v102, 0
	v_mov_b32_e32 v109, 0
	v_mov_b32_e32 v108, 0
	v_mov_b32_e32 v111, 0
	v_mov_b32_e32 v110, 0
	v_mov_b32_e32 v85, 0
	v_mov_b32_e32 v84, 0
	v_mov_b32_e32 v87, 0
	v_mov_b32_e32 v86, 0
	v_mov_b32_e32 v93, 0
	v_mov_b32_e32 v92, 0
	v_mov_b32_e32 v95, 0
	v_mov_b32_e32 v94, 0
	v_mov_b32_e32 v73, 0
	v_mov_b32_e32 v72, 0
	v_mov_b32_e32 v75, 0
	v_mov_b32_e32 v74, 0
	v_mov_b32_e32 v77, 0
	v_mov_b32_e32 v76, 0
	v_mov_b32_e32 v79, 0
	v_mov_b32_e32 v78, 0
	v_mov_b32_e32 v139, 0
	v_mov_b32_e32 v138, 0
	v_mov_b32_e32 v141, 0
	v_mov_b32_e32 v140, 0
	v_mov_b32_e32 v143, 0
	v_mov_b32_e32 v142, 0
	v_mov_b32_e32 v145, 0
	v_mov_b32_e32 v144, 0
	v_mov_b32_e32 v113, 0
	v_mov_b32_e32 v112, 0
	v_mov_b32_e32 v115, 0
	v_mov_b32_e32 v114, 0
	v_mov_b32_e32 v117, 0
	v_mov_b32_e32 v116, 0
	v_mov_b32_e32 v119, 0
	v_mov_b32_e32 v118, 0
	v_mov_b32_e32 v97, 0
	v_mov_b32_e32 v96, 0
	v_mov_b32_e32 v99, 0
	v_mov_b32_e32 v98, 0
	v_mov_b32_e32 v105, 0
	v_mov_b32_e32 v104, 0
	v_mov_b32_e32 v107, 0
	v_mov_b32_e32 v106, 0
	v_mov_b32_e32 v71, 0
	v_mov_b32_e32 v70, 0
	v_mov_b32_e32 v69, 0
	v_mov_b32_e32 v68, 0
	v_mov_b32_e32 v67, 0
	v_mov_b32_e32 v66, 0
	v_mov_b32_e32 v65, 0
	v_mov_b32_e32 v64, 0
	v_mov_b32_e32 v63, 0
	v_mov_b32_e32 v62, 0
	v_mov_b32_e32 v61, 0
	v_mov_b32_e32 v60, 0
	v_mov_b32_e32 v59, 0
	v_mov_b32_e32 v58, 0
	v_mov_b32_e32 v57, 0
	v_mov_b32_e32 v56, 0
	v_mov_b32_e32 v37, 0
	v_mov_b32_e32 v36, 0
	v_mov_b32_e32 v39, 0
	v_mov_b32_e32 v38, 0
	v_mov_b32_e32 v45, 0
	v_mov_b32_e32 v44, 0
	v_mov_b32_e32 v47, 0
	v_mov_b32_e32 v46, 0
	v_mov_b32_e32 v21, 0
	v_mov_b32_e32 v20, 0
	v_mov_b32_e32 v23, 0
	v_mov_b32_e32 v22, 0
	v_mov_b32_e32 v29, 0
	v_mov_b32_e32 v28, 0
	v_mov_b32_e32 v31, 0
	v_mov_b32_e32 v30, 0
	v_mov_b32_e32 v9, 0
	v_mov_b32_e32 v8, 0
	v_mov_b32_e32 v11, 0
	v_mov_b32_e32 v10, 0
	v_mov_b32_e32 v13, 0
	v_mov_b32_e32 v12, 0
	v_mov_b32_e32 v15, 0
	v_mov_b32_e32 v14, 0
	v_mov_b32_e32 v81, 0
	v_mov_b32_e32 v80, 0
	v_mov_b32_e32 v83, 0
	v_mov_b32_e32 v82, 0
	v_mov_b32_e32 v89, 0
	v_mov_b32_e32 v88, 0
	v_mov_b32_e32 v91, 0
	v_mov_b32_e32 v90, 0
	v_mov_b32_e32 v49, 0
	v_mov_b32_e32 v48, 0
	v_mov_b32_e32 v51, 0
	v_mov_b32_e32 v50, 0
	v_mov_b32_e32 v53, 0
	v_mov_b32_e32 v52, 0
	v_mov_b32_e32 v55, 0
	v_mov_b32_e32 v54, 0
	v_mov_b32_e32 v33, 0
	v_mov_b32_e32 v32, 0
	v_mov_b32_e32 v35, 0
	v_mov_b32_e32 v34, 0
	v_mov_b32_e32 v41, 0
	v_mov_b32_e32 v40, 0
	v_mov_b32_e32 v43, 0
	v_mov_b32_e32 v42, 0
	v_mov_b32_e32 v7, 0
	v_mov_b32_e32 v6, 0
	v_mov_b32_e32 v5, 0
	v_mov_b32_e32 v4, 0
	v_mov_b32_e32 v3, 0
	v_mov_b32_e32 v2, 0
	v_mov_b32_e32 v1, 0
	v_mov_b32_e32 v0, 0
	s_cbranch_vccnz .LBB0_1110
	s_add_u32 s51, s36, 0x100
	v_mov_b32_e32 v0, 0
	s_addc_u32 s52, s37, 0
	s_mov_b32 s40, 0
	v_mov_b32_e32 v1, v0
	v_mov_b32_e32 v2, v0
	v_mov_b32_e32 v3, v0
	v_mov_b32_e32 v4, v0
	v_mov_b32_e32 v5, v0
	v_mov_b32_e32 v6, v0
	v_mov_b32_e32 v7, v0
	v_mov_b32_e32 v8, v0
	v_mov_b32_e32 v9, v0
	v_mov_b32_e32 v10, v0
	v_mov_b32_e32 v11, v0
	v_mov_b32_e32 v12, v0
	v_mov_b32_e32 v13, v0
	v_mov_b32_e32 v14, v0
	v_mov_b32_e32 v15, v0
	v_mov_b32_e32 v20, v0
	v_mov_b32_e32 v21, v0
	v_mov_b32_e32 v22, v0
	v_mov_b32_e32 v23, v0
	v_mov_b32_e32 v28, v0
	v_mov_b32_e32 v29, v0
	v_mov_b32_e32 v30, v0
	v_mov_b32_e32 v31, v0
	v_mov_b32_e32 v36, v0
	v_mov_b32_e32 v37, v0
	v_mov_b32_e32 v38, v0
	v_mov_b32_e32 v39, v0
	v_mov_b32_e32 v44, v0
	v_mov_b32_e32 v45, v0
	v_mov_b32_e32 v46, v0
	v_mov_b32_e32 v47, v0
	v_mov_b32_e32 v16, v0
	v_mov_b32_e32 v17, v0
	v_mov_b32_e32 v18, v0
	v_mov_b32_e32 v19, v0
	v_mov_b32_e32 v24, v0
	v_mov_b32_e32 v25, v0
	v_mov_b32_e32 v26, v0
	v_mov_b32_e32 v27, v0
	v_mov_b32_e32 v32, v0
	v_mov_b32_e32 v33, v0
	v_mov_b32_e32 v34, v0
	v_mov_b32_e32 v35, v0
	v_mov_b32_e32 v40, v0
	v_mov_b32_e32 v41, v0
	v_mov_b32_e32 v42, v0
	v_mov_b32_e32 v43, v0
	v_mov_b32_e32 v48, v0
	v_mov_b32_e32 v49, v0
	v_mov_b32_e32 v50, v0
	v_mov_b32_e32 v51, v0
	v_mov_b32_e32 v52, v0
	v_mov_b32_e32 v53, v0
	v_mov_b32_e32 v54, v0
	v_mov_b32_e32 v55, v0
	v_mov_b32_e32 v56, v0
	v_mov_b32_e32 v57, v0
	v_mov_b32_e32 v58, v0
	v_mov_b32_e32 v59, v0
	v_mov_b32_e32 v60, v0
	v_mov_b32_e32 v61, v0
	v_mov_b32_e32 v62, v0
	v_mov_b32_e32 v63, v0
	v_mov_b32_e32 v64, v0
	v_mov_b32_e32 v65, v0
	v_mov_b32_e32 v66, v0
	v_mov_b32_e32 v67, v0
	v_mov_b32_e32 v68, v0
	v_mov_b32_e32 v69, v0
	v_mov_b32_e32 v70, v0
	v_mov_b32_e32 v71, v0
	v_mov_b32_e32 v72, v0
	v_mov_b32_e32 v73, v0
	v_mov_b32_e32 v74, v0
	v_mov_b32_e32 v75, v0
	v_mov_b32_e32 v76, v0
	v_mov_b32_e32 v77, v0
	v_mov_b32_e32 v78, v0
	v_mov_b32_e32 v79, v0
	v_mov_b32_e32 v84, v0
	v_mov_b32_e32 v85, v0
	v_mov_b32_e32 v86, v0
	v_mov_b32_e32 v87, v0
	v_mov_b32_e32 v92, v0
	v_mov_b32_e32 v93, v0
	v_mov_b32_e32 v94, v0
	v_mov_b32_e32 v95, v0
	v_mov_b32_e32 v100, v0
	v_mov_b32_e32 v101, v0
	v_mov_b32_e32 v102, v0
	v_mov_b32_e32 v103, v0
	v_mov_b32_e32 v108, v0
	v_mov_b32_e32 v109, v0
	v_mov_b32_e32 v110, v0
	v_mov_b32_e32 v111, v0
	v_mov_b32_e32 v80, v0
	v_mov_b32_e32 v81, v0
	v_mov_b32_e32 v82, v0
	v_mov_b32_e32 v83, v0
	v_mov_b32_e32 v88, v0
	v_mov_b32_e32 v89, v0
	v_mov_b32_e32 v90, v0
	v_mov_b32_e32 v91, v0
	v_mov_b32_e32 v96, v0
	v_mov_b32_e32 v97, v0
	v_mov_b32_e32 v98, v0
	v_mov_b32_e32 v99, v0
	v_mov_b32_e32 v104, v0
	v_mov_b32_e32 v105, v0
	v_mov_b32_e32 v106, v0
	v_mov_b32_e32 v107, v0
	v_mov_b32_e32 v112, v0
	v_mov_b32_e32 v113, v0
	v_mov_b32_e32 v114, v0
	v_mov_b32_e32 v115, v0
	v_mov_b32_e32 v116, v0
	v_mov_b32_e32 v117, v0
	v_mov_b32_e32 v118, v0
	v_mov_b32_e32 v119, v0
	v_mov_b32_e32 v120, v0
	v_mov_b32_e32 v121, v0
	v_mov_b32_e32 v122, v0
	v_mov_b32_e32 v123, v0
	v_mov_b32_e32 v124, v0
	v_mov_b32_e32 v125, v0
	v_mov_b32_e32 v126, v0
	v_mov_b32_e32 v127, v0
	.p2align	6
